# all four GEMM epilogues de-serialised: residual/ss loads hoisted in batches, out-proj epilogue rewritten with 3 load batches
# speedup vs baseline: 1.0136x; 1.0136x over previous
; #define PG8_STAGE(bufoff, gbase, voff) do { _Pragma("unroll") for (int _i = 0; _i < 2; ++_i) \
;         __builtin_amdgcn_global_load_lds((const unsigned*)((const char*)(gbase) + (voff)[_i]), (PG8_LAS unsigned*)(lds + (bufoff) + ldsw + _i * 8192), 16, 0, 0); } while (0)
; #define PG8_LDA(dst, b, h) do { _Pragma("unroll") for (int m = 0; m < 4; ++m) _Pragma("unroll") for (int k = 0; k < 2; ++k) dst[m][k] = *(const PG8_LAS bf16x8*)(lds + PG8_SA(b, h) + aoff + m * 2048 + k * 1024); } while (0)
; #define PG8_LDB(dst, b, h) do { _Pragma("unroll") for (int n = 0; n < 2; ++n) _Pragma("unroll") for (int k = 0; k < 2; ++k) dst[n][k] = *(const PG8_LAS bf16x8*)(lds + PG8_SB(b, h) + boff + n * 2048 + k * 1024); } while (0)
; #define PG8_MMA(ai, bj, At, Bt) do { __builtin_amdgcn_s_setprio(1); _Pragma("unroll") for (int m = 0; m < 4; ++m) _Pragma("unroll") for (int n = 0; n < 2; ++n) _Pragma("unroll") for (int k = 0; k < 2; ++k) \
;         acc[ai][bj][m][n] = __builtin_amdgcn_mfma_f32_16x16x32_bf16(Bt[n][k], At[m][k], acc[ai][bj][m][n], 0, 0, 0); __builtin_amdgcn_s_setprio(0); } while (0)
; #define PG8_WAIT_V(n) asm volatile("s_waitcnt vmcnt(" #n ")" ::: "memory")
; #define PG8_WAIT_L(n) asm volatile("s_waitcnt lgkmcnt(" #n ")" ::: "memory")
; #define PG8_BAR __builtin_amdgcn_s_barrier()
; #define PG8_SCHED __builtin_amdgcn_sched_barrier(0)
; template <class Epi, class Sched, bool ALIGN_EPI = false, bool SP2 = false>
; __device__ __forceinline__ void gemm_phase(PG8_LAS unsigned char* lds, const Gemm g, const Sched& S, const Epi& E) {
;     ...
;             PG8_LDB(B0, 0, 0); PG8_LDB(B1, 0, 1); PG8_SCHED; PG8_LDA(At, 0, 0); PG8_STAGE(PG8_SA(1, 1), a1 + hstep, voffA);
;             PG8_WAIT_V(8); PG8_WAIT_L(0); PG8_BAR; PG8_MMA(0, 0, At, B0); PG8_MMA(0, 1, At, B1); PG8_BAR; PG8_SCHED;
;             PG8_LDA(At, 0, 1); PG8_STAGE(PG8_SB(0, 0), b2, voffB); PG8_STAGE(PG8_SB(0, 1), b2 + hstep, voffB); PG8_STAGE(PG8_SA(0, 0), a2, voffA);
;             PG8_WAIT_V(8); PG8_WAIT_L(0); PG8_BAR; PG8_MMA(1, 0, At, B0); PG8_MMA(1, 1, At, B1); PG8_BAR; PG8_SCHED;
.LBB0_1379:
	s_add_u32 s44, s42, 0xfffc0080
	s_addc_u32 s45, s43, -1
	s_add_i32 s64, 0, 0x10000
	s_cmp_eq_u32 s63, 12
	s_cselect_b32 s47, s19, s45
	s_cselect_b32 s46, s59, s44
	v_add_u32_e32 v140, s64, v173
	s_cselect_b32 s45, s17, s62
	s_cselect_b32 s44, s60, s61
	s_add_i32 s66, 0, 0x14000
	ds_read_b128 v[130:133], v140
	ds_read_b128 v[134:137], v140 offset:1024
	ds_read_b128 v[160:163], v140 offset:2048
	ds_read_b128 v[164:167], v140 offset:3072
	v_add_u32_e32 v140, s66, v173
	ds_read_b128 v[168:171], v140
	ds_read_b128 v[176:179], v140 offset:1024
	ds_read_b128 v[180:183], v140 offset:2048
	ds_read_b128 v[184:187], v140 offset:3072
	v_lshl_add_u64 v[140:141], s[42:43], 0, v[156:157]
	s_add_i32 m0, s50, 0xc000
	ds_read_b128 v[188:191], v175
	ds_read_b128 v[192:195], v175 offset:1024
	ds_read_b128 v[196:199], v175 offset:2048
	ds_read_b128 v[200:203], v175 offset:3072
	ds_read_b128 v[204:207], v175 offset:4096
	ds_read_b128 v[220:223], v175 offset:5120
	ds_read_b128 v[224:227], v175 offset:6144
	ds_read_b128 v[228:231], v175 offset:7168
	global_load_lds_dwordx4 v[140:141], off
	v_lshl_add_u64 v[140:141], s[42:43], 0, v[158:159]
	s_add_i32 m0, s50, 0xe000
	s_nop 0
	global_load_lds_dwordx4 v[140:141], off
	s_waitcnt vmcnt(8)
	s_waitcnt lgkmcnt(0)
	s_barrier
	s_setprio 1
	s_waitcnt lgkmcnt(0)
	v_mfma_f32_16x16x32_bf16 v[126:129], v[130:133], v[188:191], v[126:129]
	v_mfma_f32_16x16x32_bf16 v[122:125], v[160:163], v[188:191], v[122:125]
	v_mfma_f32_16x16x32_bf16 v[110:113], v[130:133], v[196:199], v[110:113]
	v_mfma_f32_16x16x32_bf16 v[106:109], v[160:163], v[196:199], v[106:109]
	v_mfma_f32_16x16x32_bf16 v[94:97], v[130:133], v[204:207], v[94:97]
	v_mfma_f32_16x16x32_bf16 v[90:93], v[160:163], v[204:207], v[90:93]
	v_mfma_f32_16x16x32_bf16 v[78:81], v[130:133], v[224:227], v[78:81]
	v_mfma_f32_16x16x32_bf16 v[74:77], v[160:163], v[224:227], v[74:77]
	v_mfma_f32_16x16x32_bf16 v[126:129], v[134:137], v[192:195], v[126:129]
	v_mfma_f32_16x16x32_bf16 v[122:125], v[164:167], v[192:195], v[122:125]
	v_mfma_f32_16x16x32_bf16 v[110:113], v[134:137], v[200:203], v[110:113]
	v_mfma_f32_16x16x32_bf16 v[106:109], v[164:167], v[200:203], v[106:109]
	v_mfma_f32_16x16x32_bf16 v[94:97], v[134:137], v[220:223], v[94:97]
	v_mfma_f32_16x16x32_bf16 v[90:93], v[164:167], v[220:223], v[90:93]
	v_mfma_f32_16x16x32_bf16 v[78:81], v[134:137], v[228:231], v[78:81]
	v_mfma_f32_16x16x32_bf16 v[74:77], v[164:167], v[228:231], v[74:77]
	s_setprio 0
	s_setprio 1
	v_mfma_f32_16x16x32_bf16 v[118:121], v[168:171], v[188:191], v[118:121]
	v_mfma_f32_16x16x32_bf16 v[114:117], v[180:183], v[188:191], v[114:117]
	v_mfma_f32_16x16x32_bf16 v[102:105], v[168:171], v[196:199], v[102:105]
	v_mfma_f32_16x16x32_bf16 v[98:101], v[180:183], v[196:199], v[98:101]
	v_mfma_f32_16x16x32_bf16 v[86:89], v[168:171], v[204:207], v[86:89]
	v_mfma_f32_16x16x32_bf16 v[82:85], v[180:183], v[204:207], v[82:85]
	v_mfma_f32_16x16x32_bf16 v[70:73], v[168:171], v[224:227], v[70:73]
	v_mfma_f32_16x16x32_bf16 v[66:69], v[180:183], v[224:227], v[66:69]
	v_mfma_f32_16x16x32_bf16 v[118:121], v[176:179], v[192:195], v[118:121]
	v_mfma_f32_16x16x32_bf16 v[114:117], v[184:187], v[192:195], v[114:117]
	v_mfma_f32_16x16x32_bf16 v[102:105], v[176:179], v[200:203], v[102:105]
	v_mfma_f32_16x16x32_bf16 v[98:101], v[184:187], v[200:203], v[98:101]
	v_mfma_f32_16x16x32_bf16 v[86:89], v[176:179], v[220:223], v[86:89]
	v_mfma_f32_16x16x32_bf16 v[82:85], v[184:187], v[220:223], v[82:85]
	v_mfma_f32_16x16x32_bf16 v[70:73], v[176:179], v[228:231], v[70:73]
	v_mfma_f32_16x16x32_bf16 v[66:69], v[184:187], v[228:231], v[66:69]
	s_setprio 0
	s_barrier
	s_add_i32 s64, s64, s49
	v_lshl_add_u64 v[140:141], s[44:45], 0, v[0:1]
	s_mov_b32 m0, s64
	ds_read_b128 v[188:191], v175 offset:16384
	ds_read_b128 v[192:195], v175 offset:17408
	ds_read_b128 v[196:199], v175 offset:18432
	ds_read_b128 v[200:203], v175 offset:19456
	ds_read_b128 v[204:207], v175 offset:20480
	ds_read_b128 v[220:223], v175 offset:21504
	ds_read_b128 v[224:227], v175 offset:22528
	ds_read_b128 v[228:231], v175 offset:23552
	global_load_lds_dwordx4 v[140:141], off
	s_add_i32 m0, s64, 0x2000
	s_add_u32 s64, s44, 0x40000
	v_lshl_add_u64 v[146:147], s[44:45], 0, v[150:151]
	s_addc_u32 s65, s45, 0
	s_add_i32 s66, s66, s49
	global_load_lds_dwordx4 v[146:147], off
	v_lshl_add_u64 v[210:211], s[64:65], 0, v[0:1]
	s_mov_b32 m0, s66
	v_lshl_add_u64 v[212:213], s[46:47], 0, v[152:153]
	global_load_lds_dwordx4 v[210:211], off
	v_lshl_add_u64 v[210:211], s[64:65], 0, v[150:151]
	s_add_i32 m0, s66, 0x2000
	s_nop 0
	global_load_lds_dwordx4 v[210:211], off
	v_lshl_add_u64 v[210:211], s[46:47], 0, v[154:155]
	s_mov_b32 m0, s50
	s_nop 0
	global_load_lds_dwordx4 v[210:211], off
	s_mov_b32 m0, s51
	s_nop 0
	global_load_lds_dwordx4 v[212:213], off
	s_waitcnt vmcnt(8)
	s_waitcnt lgkmcnt(0)
	s_barrier
; #define PG8_STAGE(bufoff, gbase, voff) do { _Pragma("unroll") for (int _i = 0; _i < 2; ++_i) \
;         __builtin_amdgcn_global_load_lds((const unsigned*)((const char*)(gbase) + (voff)[_i]), (PG8_LAS unsigned*)(lds + (bufoff) + ldsw + _i * 8192), 16, 0, 0); } while (0)
; #define PG8_LDA(dst, b, h) do { _Pragma("unroll") for (int m = 0; m < 4; ++m) _Pragma("unroll") for (int k = 0; k < 2; ++k) dst[m][k] = *(const PG8_LAS bf16x8*)(lds + PG8_SA(b, h) + aoff + m * 2048 + k * 1024); } while (0)
; #define PG8_LDB(dst, b, h) do { _Pragma("unroll") for (int n = 0; n < 2; ++n) _Pragma("unroll") for (int k = 0; k < 2; ++k) dst[n][k] = *(const PG8_LAS bf16x8*)(lds + PG8_SB(b, h) + boff + n * 2048 + k * 1024); } while (0)
; #define PG8_MMA(ai, bj, At, Bt) do { __builtin_amdgcn_s_setprio(1); _Pragma("unroll") for (int m = 0; m < 4; ++m) _Pragma("unroll") for (int n = 0; n < 2; ++n) _Pragma("unroll") for (int k = 0; k < 2; ++k) \
;         acc[ai][bj][m][n] = __builtin_amdgcn_mfma_f32_16x16x32_bf16(Bt[n][k], At[m][k], acc[ai][bj][m][n], 0, 0, 0); __builtin_amdgcn_s_setprio(0); } while (0)
; #define PG8_WAIT_V(n) asm volatile("s_waitcnt vmcnt(" #n ")" ::: "memory")
; #define PG8_WAIT_L(n) asm volatile("s_waitcnt lgkmcnt(" #n ")" ::: "memory")
; #define PG8_BAR __builtin_amdgcn_s_barrier()
; #define PG8_SCHED __builtin_amdgcn_sched_barrier(0)
; template <class Epi, class Sched, bool ALIGN_EPI = false, bool SP2 = false>
; __device__ __forceinline__ void gemm_phase(PG8_LAS unsigned char* lds, const Gemm g, const Sched& S, const Epi& E) {
;     ...
;             PG8_WAIT_V(8); PG8_WAIT_L(0); PG8_BAR; PG8_MMA(1, 0, At, B0); PG8_MMA(1, 1, At, B1); PG8_BAR; PG8_SCHED;
;             PG8_LDB(B0, 1, 0); PG8_LDB(B1, 1, 1); PG8_SCHED; PG8_LDA(At, 1, 0); PG8_STAGE(PG8_SA(0, 1), a2 + hstep, voffA);
;             PG8_WAIT_V(8); PG8_WAIT_L(0); PG8_BAR; PG8_MMA(0, 0, At, B0); PG8_MMA(0, 1, At, B1); PG8_BAR; PG8_SCHED;
	s_setprio 1
	s_waitcnt lgkmcnt(0)
	v_mfma_f32_16x16x32_bf16 v[62:65], v[130:133], v[188:191], v[62:65]
	v_mfma_f32_16x16x32_bf16 v[58:61], v[160:163], v[188:191], v[58:61]
	v_mfma_f32_16x16x32_bf16 v[46:49], v[130:133], v[196:199], v[46:49]
	v_mfma_f32_16x16x32_bf16 v[42:45], v[160:163], v[196:199], v[42:45]
	v_mfma_f32_16x16x32_bf16 v[30:33], v[130:133], v[204:207], v[30:33]
	v_mfma_f32_16x16x32_bf16 v[26:29], v[160:163], v[204:207], v[26:29]
	v_mfma_f32_16x16x32_bf16 v[14:17], v[130:133], v[224:227], v[14:17]
	v_mfma_f32_16x16x32_bf16 v[10:13], v[160:163], v[224:227], v[10:13]
	v_mfma_f32_16x16x32_bf16 v[62:65], v[134:137], v[192:195], v[62:65]
	v_mfma_f32_16x16x32_bf16 v[58:61], v[164:167], v[192:195], v[58:61]
	v_mfma_f32_16x16x32_bf16 v[46:49], v[134:137], v[200:203], v[46:49]
	v_mfma_f32_16x16x32_bf16 v[42:45], v[164:167], v[200:203], v[42:45]
	v_mfma_f32_16x16x32_bf16 v[30:33], v[134:137], v[220:223], v[30:33]
	v_mfma_f32_16x16x32_bf16 v[26:29], v[164:167], v[220:223], v[26:29]
	v_mfma_f32_16x16x32_bf16 v[14:17], v[134:137], v[228:231], v[14:17]
	v_mfma_f32_16x16x32_bf16 v[10:13], v[164:167], v[228:231], v[10:13]
	s_setprio 0
	s_setprio 1
	v_mfma_f32_16x16x32_bf16 v[54:57], v[168:171], v[188:191], v[54:57]
	v_mfma_f32_16x16x32_bf16 v[50:53], v[180:183], v[188:191], v[50:53]
	v_mfma_f32_16x16x32_bf16 v[38:41], v[168:171], v[196:199], v[38:41]
	v_mfma_f32_16x16x32_bf16 v[34:37], v[180:183], v[196:199], v[34:37]
	v_mfma_f32_16x16x32_bf16 v[22:25], v[168:171], v[204:207], v[22:25]
	v_mfma_f32_16x16x32_bf16 v[18:21], v[180:183], v[204:207], v[18:21]
	v_mfma_f32_16x16x32_bf16 v[6:9], v[168:171], v[224:227], v[6:9]
	v_mfma_f32_16x16x32_bf16 v[2:5], v[180:183], v[224:227], v[2:5]
	v_mfma_f32_16x16x32_bf16 v[54:57], v[176:179], v[192:195], v[54:57]
	v_mfma_f32_16x16x32_bf16 v[50:53], v[184:187], v[192:195], v[50:53]
	v_mfma_f32_16x16x32_bf16 v[38:41], v[176:179], v[200:203], v[38:41]
	v_mfma_f32_16x16x32_bf16 v[34:37], v[184:187], v[200:203], v[34:37]
	v_mfma_f32_16x16x32_bf16 v[22:25], v[176:179], v[220:223], v[22:25]
	v_mfma_f32_16x16x32_bf16 v[18:21], v[184:187], v[220:223], v[18:21]
	v_mfma_f32_16x16x32_bf16 v[6:9], v[176:179], v[228:231], v[6:9]
	v_mfma_f32_16x16x32_bf16 v[2:5], v[184:187], v[228:231], v[2:5]
	s_setprio 0
	s_barrier
	s_add_i32 s64, 0, 0x18000
	s_add_i32 s65, 0, 0x1c000
	v_add_u32_e32 v164, s64, v173
	v_add_u32_e32 v184, s65, v173
	ds_read_b128 v[130:133], v164
	ds_read_b128 v[134:137], v164 offset:1024
	ds_read_b128 v[160:163], v164 offset:2048
	ds_read_b128 v[164:167], v164 offset:3072
	ds_read_b128 v[168:171], v184
	ds_read_b128 v[176:179], v184 offset:1024
	ds_read_b128 v[180:183], v184 offset:2048
	ds_read_b128 v[184:187], v184 offset:3072
	s_add_u32 s46, s46, 0x40000
	s_addc_u32 s47, s47, 0
	s_mov_b32 m0, s52
	v_lshl_add_u64 v[218:219], s[46:47], 0, v[154:155]
	ds_read_b128 v[188:191], v175 offset:32768
	ds_read_b128 v[192:195], v175 offset:33792
	ds_read_b128 v[196:199], v175 offset:34816
	ds_read_b128 v[200:203], v175 offset:35840
	ds_read_b128 v[204:207], v175 offset:36864
	ds_read_b128 v[220:223], v175 offset:37888
	ds_read_b128 v[224:227], v175 offset:38912
	ds_read_b128 v[228:231], v175 offset:39936
	global_load_lds_dwordx4 v[218:219], off
	v_lshl_add_u64 v[218:219], s[46:47], 0, v[152:153]
	s_mov_b32 m0, s53
	s_nop 0
	global_load_lds_dwordx4 v[218:219], off
	s_waitcnt vmcnt(8)
	s_waitcnt lgkmcnt(0)
	s_barrier
	s_setprio 1
	s_waitcnt lgkmcnt(0)
	v_mfma_f32_16x16x32_bf16 v[126:129], v[130:133], v[188:191], v[126:129]
	v_mfma_f32_16x16x32_bf16 v[122:125], v[160:163], v[188:191], v[122:125]
	v_mfma_f32_16x16x32_bf16 v[110:113], v[130:133], v[196:199], v[110:113]
	v_mfma_f32_16x16x32_bf16 v[106:109], v[160:163], v[196:199], v[106:109]
	v_mfma_f32_16x16x32_bf16 v[94:97], v[130:133], v[204:207], v[94:97]
	v_mfma_f32_16x16x32_bf16 v[90:93], v[160:163], v[204:207], v[90:93]
	v_mfma_f32_16x16x32_bf16 v[78:81], v[130:133], v[224:227], v[78:81]
	v_mfma_f32_16x16x32_bf16 v[74:77], v[160:163], v[224:227], v[74:77]
	v_mfma_f32_16x16x32_bf16 v[126:129], v[134:137], v[192:195], v[126:129]
	v_mfma_f32_16x16x32_bf16 v[122:125], v[164:167], v[192:195], v[122:125]
	v_mfma_f32_16x16x32_bf16 v[110:113], v[134:137], v[200:203], v[110:113]
	v_mfma_f32_16x16x32_bf16 v[106:109], v[164:167], v[200:203], v[106:109]
	v_mfma_f32_16x16x32_bf16 v[94:97], v[134:137], v[220:223], v[94:97]
	v_mfma_f32_16x16x32_bf16 v[90:93], v[164:167], v[220:223], v[90:93]
	v_mfma_f32_16x16x32_bf16 v[78:81], v[134:137], v[228:231], v[78:81]
	v_mfma_f32_16x16x32_bf16 v[74:77], v[164:167], v[228:231], v[74:77]
	s_setprio 0
	s_setprio 1
	v_mfma_f32_16x16x32_bf16 v[118:121], v[168:171], v[188:191], v[118:121]
	v_mfma_f32_16x16x32_bf16 v[114:117], v[180:183], v[188:191], v[114:117]
	v_mfma_f32_16x16x32_bf16 v[102:105], v[168:171], v[196:199], v[102:105]
	v_mfma_f32_16x16x32_bf16 v[98:101], v[180:183], v[196:199], v[98:101]
	v_mfma_f32_16x16x32_bf16 v[86:89], v[168:171], v[204:207], v[86:89]
	v_mfma_f32_16x16x32_bf16 v[82:85], v[180:183], v[204:207], v[82:85]
	v_mfma_f32_16x16x32_bf16 v[70:73], v[168:171], v[224:227], v[70:73]
	v_mfma_f32_16x16x32_bf16 v[66:69], v[180:183], v[224:227], v[66:69]
	v_mfma_f32_16x16x32_bf16 v[118:121], v[176:179], v[192:195], v[118:121]
	v_mfma_f32_16x16x32_bf16 v[114:117], v[184:187], v[192:195], v[114:117]
	v_mfma_f32_16x16x32_bf16 v[102:105], v[176:179], v[200:203], v[102:105]
	v_mfma_f32_16x16x32_bf16 v[98:101], v[184:187], v[200:203], v[98:101]
	v_mfma_f32_16x16x32_bf16 v[86:89], v[176:179], v[220:223], v[86:89]
	v_mfma_f32_16x16x32_bf16 v[82:85], v[184:187], v[220:223], v[82:85]
	v_mfma_f32_16x16x32_bf16 v[70:73], v[176:179], v[228:231], v[70:73]
	v_mfma_f32_16x16x32_bf16 v[66:69], v[184:187], v[228:231], v[66:69]
	s_setprio 0
	s_barrier
; #define PG8_STAGE(bufoff, gbase, voff) do { _Pragma("unroll") for (int _i = 0; _i < 2; ++_i) \
;         __builtin_amdgcn_global_load_lds((const unsigned*)((const char*)(gbase) + (voff)[_i]), (PG8_LAS unsigned*)(lds + (bufoff) + ldsw + _i * 8192), 16, 0, 0); } while (0)
; #define PG8_LDA(dst, b, h) do { _Pragma("unroll") for (int m = 0; m < 4; ++m) _Pragma("unroll") for (int k = 0; k < 2; ++k) dst[m][k] = *(const PG8_LAS bf16x8*)(lds + PG8_SA(b, h) + aoff + m * 2048 + k * 1024); } while (0)
; #define PG8_MMA(ai, bj, At, Bt) do { __builtin_amdgcn_s_setprio(1); _Pragma("unroll") for (int m = 0; m < 4; ++m) _Pragma("unroll") for (int n = 0; n < 2; ++n) _Pragma("unroll") for (int k = 0; k < 2; ++k) \
;         acc[ai][bj][m][n] = __builtin_amdgcn_mfma_f32_16x16x32_bf16(Bt[n][k], At[m][k], acc[ai][bj][m][n], 0, 0, 0); __builtin_amdgcn_s_setprio(0); } while (0)
; #define PG8_WAIT_V(n) asm volatile("s_waitcnt vmcnt(" #n ")" ::: "memory")
; #define PG8_BAR __builtin_amdgcn_s_barrier()
; template <class Epi, class Sched, bool ALIGN_EPI = false, bool SP2 = false>
; __device__ __forceinline__ void gemm_phase(PG8_LAS unsigned char* lds, const Gemm g, const Sched& S, const Epi& E) {
;     ...
;             PG8_LDA(At, 1, 1); PG8_STAGE(PG8_SB(1, 0), b3, voffB); PG8_STAGE(PG8_SB(1, 1), b3 + hstep, voffB); PG8_STAGE(PG8_SA(1, 0), a3, voffA);
;             PG8_WAIT_V(8); PG8_WAIT_L(0); PG8_BAR; PG8_MMA(1, 0, At, B0); PG8_MMA(1, 1, At, B1); PG8_BAR; PG8_SCHED;
;     __device__ __forceinline__ void operator()(const pg8::f32x4 (&acc)[2][2][4][2], const pg8::Unit& u, int wr, int wc, int fr, int fq) const {
;         const int row0 = u.pm * 256 + wr * 64 + fr, col0 = u.pn * 256 + wc * 32 + 8 * fq;
; #pragma unroll
;         for (int ai = 0; ai < 2; ++ai)
; #pragma unroll
;             for (int m = 0; m < 4; ++m) {
;                 const int row = row0 + ai * 128 + m * 16; const size_t off = (size_t)row * DM + col0; float sq = 0.f;
; #pragma unroll
;                 for (int bj = 0; bj < 2; ++bj) { const size_t o = off + bj * 128; f32x4 xa, xc;
;                     if (xin) { xa = *(const f32x4*)(xin + o); xc = *(const f32x4*)(xin + o + 4); }
;                     else { const u32x4 r4 = *(const u32x4*)(xin_b + o); xa[0] = blo(r4.x); xa[1] = bhi(r4.x); xa[2] = blo(r4.y); xa[3] = bhi(r4.y); xc[0] = blo(r4.z); xc[1] = bhi(r4.z); xc[2] = blo(r4.w); xc[3] = bhi(r4.w); }
	s_add_i32 s46, s64, s49
	v_lshl_add_u64 v[140:141], v[140:141], 0, s[20:21]
	s_mov_b32 m0, s46
	ds_read_b128 v[188:191], v175 offset:49152
	ds_read_b128 v[192:195], v175 offset:50176
	ds_read_b128 v[196:199], v175 offset:51200
	ds_read_b128 v[200:203], v175 offset:52224
	ds_read_b128 v[204:207], v175 offset:53248
	ds_read_b128 v[220:223], v175 offset:54272
	ds_read_b128 v[224:227], v175 offset:55296
	ds_read_b128 v[228:231], v175 offset:56320
	global_load_lds_dwordx4 v[140:141], off
	s_add_i32 m0, s46, 0x2000
	s_add_u32 s44, s44, 0x40080
	v_lshl_add_u64 v[140:141], v[146:147], 0, s[20:21]
	s_addc_u32 s45, s45, 0
	s_add_i32 s46, s65, s49
	global_load_lds_dwordx4 v[140:141], off
	v_lshl_add_u64 v[140:141], s[44:45], 0, v[0:1]
	s_mov_b32 m0, s46
	s_nop 0
	global_load_lds_dwordx4 v[140:141], off
	v_lshl_add_u64 v[140:141], s[44:45], 0, v[150:151]
	s_add_i32 m0, s46, 0x2000
	s_nop 0
	global_load_lds_dwordx4 v[140:141], off
	v_lshl_add_u64 v[140:141], v[210:211], 0, s[20:21]
	s_mov_b32 m0, s55
	s_nop 0
	global_load_lds_dwordx4 v[140:141], off
	v_lshl_add_u64 v[140:141], v[212:213], 0, s[20:21]
	s_mov_b32 m0, s56
	s_nop 0
	global_load_lds_dwordx4 v[140:141], off
	s_waitcnt vmcnt(8)
	s_waitcnt lgkmcnt(0)
	s_barrier
	s_setprio 1
	s_waitcnt lgkmcnt(0)
	v_mfma_f32_16x16x32_bf16 v[62:65], v[130:133], v[188:191], v[62:65]
	v_mfma_f32_16x16x32_bf16 v[58:61], v[160:163], v[188:191], v[58:61]
	v_mfma_f32_16x16x32_bf16 v[46:49], v[130:133], v[196:199], v[46:49]
	v_mfma_f32_16x16x32_bf16 v[42:45], v[160:163], v[196:199], v[42:45]
	v_mfma_f32_16x16x32_bf16 v[30:33], v[130:133], v[204:207], v[30:33]
	v_mfma_f32_16x16x32_bf16 v[26:29], v[160:163], v[204:207], v[26:29]
	v_mfma_f32_16x16x32_bf16 v[14:17], v[130:133], v[224:227], v[14:17]
	v_mfma_f32_16x16x32_bf16 v[10:13], v[160:163], v[224:227], v[10:13]
	v_mfma_f32_16x16x32_bf16 v[62:65], v[134:137], v[192:195], v[62:65]
	v_mfma_f32_16x16x32_bf16 v[58:61], v[164:167], v[192:195], v[58:61]
	v_mfma_f32_16x16x32_bf16 v[46:49], v[134:137], v[200:203], v[46:49]
	v_mfma_f32_16x16x32_bf16 v[42:45], v[164:167], v[200:203], v[42:45]
	v_mfma_f32_16x16x32_bf16 v[30:33], v[134:137], v[220:223], v[30:33]
	v_mfma_f32_16x16x32_bf16 v[26:29], v[164:167], v[220:223], v[26:29]
	v_mfma_f32_16x16x32_bf16 v[14:17], v[134:137], v[228:231], v[14:17]
	v_mfma_f32_16x16x32_bf16 v[10:13], v[164:167], v[228:231], v[10:13]
	s_setprio 0
	s_setprio 1
	v_mfma_f32_16x16x32_bf16 v[54:57], v[168:171], v[188:191], v[54:57]
	v_mfma_f32_16x16x32_bf16 v[50:53], v[180:183], v[188:191], v[50:53]
	v_mfma_f32_16x16x32_bf16 v[38:41], v[168:171], v[196:199], v[38:41]
	v_mfma_f32_16x16x32_bf16 v[34:37], v[180:183], v[196:199], v[34:37]
	v_mfma_f32_16x16x32_bf16 v[22:25], v[168:171], v[204:207], v[22:25]
	v_mfma_f32_16x16x32_bf16 v[18:21], v[180:183], v[204:207], v[18:21]
	v_mfma_f32_16x16x32_bf16 v[6:9], v[168:171], v[224:227], v[6:9]
	v_mfma_f32_16x16x32_bf16 v[2:5], v[180:183], v[224:227], v[2:5]
	v_mfma_f32_16x16x32_bf16 v[54:57], v[176:179], v[192:195], v[54:57]
	v_mfma_f32_16x16x32_bf16 v[50:53], v[184:187], v[192:195], v[50:53]
	v_mfma_f32_16x16x32_bf16 v[38:41], v[176:179], v[200:203], v[38:41]
	v_mfma_f32_16x16x32_bf16 v[34:37], v[184:187], v[200:203], v[34:37]
	v_mfma_f32_16x16x32_bf16 v[22:25], v[176:179], v[220:223], v[22:25]
	v_mfma_f32_16x16x32_bf16 v[18:21], v[184:187], v[220:223], v[18:21]
	v_mfma_f32_16x16x32_bf16 v[6:9], v[176:179], v[228:231], v[6:9]
	v_mfma_f32_16x16x32_bf16 v[2:5], v[184:187], v[228:231], v[2:5]
	s_setprio 0
	s_barrier
	s_add_i32 s63, s63, 2
	s_add_u32 s42, s42, 0x100
	s_addc_u32 s43, s43, 0
	s_add_u32 s61, s61, 0x100
	s_addc_u32 s62, s62, 0
	s_cmp_gt_u32 s63, 13
	s_cbranch_scc0 .LBB0_1379
	v_lshl_add_u32 v168, s58, 8, v172
	v_lshl_or_b32 v170, s57, 8, v174
	v_ashrrev_i32_e32 v169, 31, v168
	v_ashrrev_i32_e32 v171, 31, v170
	v_lshlrev_b64 v[210:211], 10, v[168:169]
	v_lshl_add_u64 v[210:211], v[210:211], 0, v[170:171]
	v_lshl_add_u64 v[226:227], v[210:211], 2, s[8:9]
	v_lshl_add_u64 v[228:229], v[210:211], 1, s[28:29]
	v_lshl_add_u64 v[230:231], v[168:169], 2, s[4:5]
	s_mov_b32 s99, 0
	s_and_b64 vcc, exec, s[14:15]
	s_cbranch_vccnz .Lo_f32_ld_0
	global_load_dwordx4 v[180:183], v[228:229], off
	global_load_dwordx4 v[188:191], v[228:229], off offset:256
	s_mov_b32 s98, 0x8000
	v_lshl_add_u64 v[212:213], v[228:229], 0, s[98:99]
	global_load_dwordx4 v[196:199], v[212:213], off
	global_load_dwordx4 v[204:207], v[212:213], off offset:256
	s_mov_b32 s98, 0x10000
	v_lshl_add_u64 v[212:213], v[228:229], 0, s[98:99]
	global_load_dwordx4 v[222:225], v[212:213], off
	global_load_dwordx4 v[164:167], v[212:213], off offset:256
	s_branch .Lo_ld_done_0
.Lo_f32_ld_0:
	global_load_dwordx4 v[176:179], v[226:227], off
	global_load_dwordx4 v[180:183], v[226:227], off offset:16
	global_load_dwordx4 v[184:187], v[226:227], off offset:512
	global_load_dwordx4 v[188:191], v[226:227], off offset:528
	s_mov_b32 s98, 0x10000
	v_lshl_add_u64 v[212:213], v[226:227], 0, s[98:99]
	global_load_dwordx4 v[192:195], v[212:213], off
	global_load_dwordx4 v[196:199], v[212:213], off offset:16
	global_load_dwordx4 v[200:203], v[212:213], off offset:512
	global_load_dwordx4 v[204:207], v[212:213], off offset:528
	s_mov_b32 s98, 0x20000
	v_lshl_add_u64 v[212:213], v[226:227], 0, s[98:99]
	global_load_dwordx4 v[218:221], v[212:213], off
	global_load_dwordx4 v[222:225], v[212:213], off offset:16
	global_load_dwordx4 v[160:163], v[212:213], off offset:512
	global_load_dwordx4 v[164:167], v[212:213], off offset:528
.Lo_ld_done_0:
	s_and_b64 vcc, exec, s[12:13]
	s_cbranch_vccz .LBB0_1382
	s_barrier
; __device__ __forceinline__ float blo(unsigned u) { return __uint_as_float(u << 16); }
; __device__ __forceinline__ float bhi(unsigned u) { return __uint_as_float(u & 0xffff0000u); }
; __device__ __forceinline__ unsigned pk2(float lo, float hi) { pk_f32x2_t v = {lo, hi}; pk_bf16x2_t b = __builtin_convertvector(v, pk_bf16x2_t); return __builtin_bit_cast(unsigned, b); }
; template <int K> __device__ __forceinline__ float swz_f(float v) { return __uint_as_float(swz_u<K>(__float_as_uint(v))); }
;     __device__ __forceinline__ void operator()(const pg8::f32x4 (&acc)[2][2][4][2], const pg8::Unit& u, int wr, int wc, int fr, int fq) const {
;         const int row0 = u.pm * 256 + wr * 64 + fr, col0 = u.pn * 256 + wc * 32 + 8 * fq;
; #pragma unroll
;         for (int ai = 0; ai < 2; ++ai)
; #pragma unroll
;             for (int m = 0; m < 4; ++m) {
;                 const int row = row0 + ai * 128 + m * 16; const size_t off = (size_t)row * DM + col0; float sq = 0.f;
; #pragma unroll
;                 for (int bj = 0; bj < 2; ++bj) { const size_t o = off + bj * 128; f32x4 xa, xc;
;                     if (xin) { xa = *(const f32x4*)(xin + o); xc = *(const f32x4*)(xin + o + 4); }
;                     else { const u32x4 r4 = *(const u32x4*)(xin_b + o); xa[0] = blo(r4.x); xa[1] = bhi(r4.x); xa[2] = blo(r4.y); xa[3] = bhi(r4.y); xc[0] = blo(r4.z); xc[1] = bhi(r4.z); xc[2] = blo(r4.w); xc[3] = bhi(r4.w); }
;                     f32x4 va, vc;
;                     va[0] = xa[0] + acc[ai][bj][m][0][0]; va[1] = xa[1] + acc[ai][bj][m][0][1]; va[2] = xa[2] + acc[ai][bj][m][0][2]; va[3] = xa[3] + acc[ai][bj][m][0][3];
;                     vc[0] = xc[0] + acc[ai][bj][m][1][0]; vc[1] = xc[1] + acc[ai][bj][m][1][1]; vc[2] = xc[2] + acc[ai][bj][m][1][2]; vc[3] = xc[3] + acc[ai][bj][m][1][3];
;                     if (xout) { *(f32x4*)(xout + o) = va; *(f32x4*)(xout + o + 4) = vc; }
;                     if (xb) { u32x4 w; w.x = pk2(va[0], va[1]); w.y = pk2(va[2], va[3]); w.z = pk2(vc[0], vc[1]); w.w = pk2(vc[2], vc[3]); *(u32x4*)(xb + o) = w; }
;                     sq += ((va[0] * va[0] + va[1] * va[1]) + (va[2] * va[2] + va[3] * va[3])) + ((vc[0] * vc[0] + vc[1] * vc[1]) + (vc[2] * vc[2] + vc[3] * vc[3])); }
;                 if (ss) { sq += swz_f<16>(sq); sq = sum32(sq); if (fq == 0) atomicAdd(ss + row, sq); }
.LBB0_1382:
	s_waitcnt vmcnt(0)
	s_and_b64 vcc, exec, s[14:15]
	s_cbranch_vccnz .Lo_common_0
	v_lshlrev_b32_e32 v176, 16, v180
	v_and_b32_e32 v177, 0xffff0000, v180
	v_lshlrev_b32_e32 v178, 16, v181
	v_and_b32_e32 v179, 0xffff0000, v181
	v_lshlrev_b32_e32 v180, 16, v182
	v_and_b32_e32 v181, 0xffff0000, v182
	v_lshlrev_b32_e32 v182, 16, v183
	v_and_b32_e32 v183, 0xffff0000, v183
	v_lshlrev_b32_e32 v184, 16, v188
	v_and_b32_e32 v185, 0xffff0000, v188
	v_lshlrev_b32_e32 v186, 16, v189
	v_and_b32_e32 v187, 0xffff0000, v189
	v_lshlrev_b32_e32 v188, 16, v190
	v_and_b32_e32 v189, 0xffff0000, v190
	v_lshlrev_b32_e32 v190, 16, v191
	v_and_b32_e32 v191, 0xffff0000, v191
	v_lshlrev_b32_e32 v192, 16, v196
	v_and_b32_e32 v193, 0xffff0000, v196
	v_lshlrev_b32_e32 v194, 16, v197
	v_and_b32_e32 v195, 0xffff0000, v197
	v_lshlrev_b32_e32 v196, 16, v198
	v_and_b32_e32 v197, 0xffff0000, v198
	v_lshlrev_b32_e32 v198, 16, v199
	v_and_b32_e32 v199, 0xffff0000, v199
	v_lshlrev_b32_e32 v200, 16, v204
	v_and_b32_e32 v201, 0xffff0000, v204
	v_lshlrev_b32_e32 v202, 16, v205
	v_and_b32_e32 v203, 0xffff0000, v205
	v_lshlrev_b32_e32 v204, 16, v206
	v_and_b32_e32 v205, 0xffff0000, v206
	v_lshlrev_b32_e32 v206, 16, v207
	v_and_b32_e32 v207, 0xffff0000, v207
	v_lshlrev_b32_e32 v218, 16, v222
	v_and_b32_e32 v219, 0xffff0000, v222
	v_lshlrev_b32_e32 v220, 16, v223
	v_and_b32_e32 v221, 0xffff0000, v223
	v_lshlrev_b32_e32 v222, 16, v224
	v_and_b32_e32 v223, 0xffff0000, v224
	v_lshlrev_b32_e32 v224, 16, v225
	v_and_b32_e32 v225, 0xffff0000, v225
	v_lshlrev_b32_e32 v160, 16, v164
	v_and_b32_e32 v161, 0xffff0000, v164
	v_lshlrev_b32_e32 v162, 16, v165
	v_and_b32_e32 v163, 0xffff0000, v165
	v_lshlrev_b32_e32 v164, 16, v166
	v_and_b32_e32 v165, 0xffff0000, v166
	v_lshlrev_b32_e32 v166, 16, v167
	v_and_b32_e32 v167, 0xffff0000, v167
.Lo_common_0:
	v_pk_add_f32 v[126:127], v[126:127], v[176:177]
	v_pk_add_f32 v[128:129], v[128:129], v[178:179]
	v_pk_add_f32 v[122:123], v[122:123], v[180:181]
	v_pk_add_f32 v[124:125], v[124:125], v[182:183]
	v_cvt_pk_bf16_f32 v176, v126, v127
	v_cvt_pk_bf16_f32 v177, v128, v129
	v_cvt_pk_bf16_f32 v178, v122, v123
	v_cvt_pk_bf16_f32 v179, v124, v125
	global_store_dwordx4 v[228:229], v[176:179], off
	v_pk_mul_f32 v[130:131], v[126:127], v[126:127]
	v_pk_mul_f32 v[132:133], v[128:129], v[128:129]
	v_pk_mul_f32 v[134:135], v[122:123], v[122:123]
	v_pk_mul_f32 v[136:137], v[124:125], v[124:125]
	v_add_f32_e32 v130, v130, v131
	v_add_f32_e32 v132, v132, v133
	v_add_f32_e32 v134, v134, v135
	v_add_f32_e32 v136, v136, v137
	v_add_f32_e32 v130, v130, v132
	v_add_f32_e32 v134, v134, v136
	v_add_f32_e32 v140, v130, v134
	v_pk_add_f32 v[118:119], v[118:119], v[184:185]
	v_pk_add_f32 v[120:121], v[120:121], v[186:187]
	v_pk_add_f32 v[114:115], v[114:115], v[188:189]
	v_pk_add_f32 v[116:117], v[116:117], v[190:191]
	v_cvt_pk_bf16_f32 v184, v118, v119
	v_cvt_pk_bf16_f32 v185, v120, v121
	v_cvt_pk_bf16_f32 v186, v114, v115
	v_cvt_pk_bf16_f32 v187, v116, v117
	global_store_dwordx4 v[228:229], v[184:187], off offset:256
	v_pk_mul_f32 v[130:131], v[118:119], v[118:119]
	v_pk_mul_f32 v[132:133], v[120:121], v[120:121]
	v_pk_mul_f32 v[134:135], v[114:115], v[114:115]
	v_pk_mul_f32 v[136:137], v[116:117], v[116:117]
	v_add_f32_e32 v130, v130, v131
	v_add_f32_e32 v132, v132, v133
	v_add_f32_e32 v134, v134, v135
	v_add_f32_e32 v136, v136, v137
	v_add_f32_e32 v130, v130, v132
	v_add_f32_e32 v134, v134, v136
	v_add_f32_e32 v130, v130, v134
	v_add_f32_e32 v140, v140, v130
	ds_swizzle_b32 v141, v140 offset:swizzle(SWAP,16)
	s_waitcnt lgkmcnt(0)
	v_add_f32_e32 v140, v140, v141
	v_mov_b32_e32 v141, v140
	s_nop 1
	v_permlane32_swap_b32_e32 v140, v141
	s_and_saveexec_b64 s[44:45], s[36:37]
	v_add_f32_e32 v140, v140, v141
	global_atomic_add_f32 v[230:231], v140, off
	s_or_b64 exec, exec, s[44:45]
	v_pk_add_f32 v[110:111], v[110:111], v[192:193]
	v_pk_add_f32 v[112:113], v[112:113], v[194:195]
	v_pk_add_f32 v[106:107], v[106:107], v[196:197]
	v_pk_add_f32 v[108:109], v[108:109], v[198:199]
	s_mov_b32 s98, 0x8000
	v_lshl_add_u64 v[212:213], v[228:229], 0, s[98:99]
	v_cvt_pk_bf16_f32 v192, v110, v111
	v_cvt_pk_bf16_f32 v193, v112, v113
	v_cvt_pk_bf16_f32 v194, v106, v107
	v_cvt_pk_bf16_f32 v195, v108, v109
	global_store_dwordx4 v[212:213], v[192:195], off
	v_pk_mul_f32 v[130:131], v[110:111], v[110:111]
	v_pk_mul_f32 v[132:133], v[112:113], v[112:113]
	v_pk_mul_f32 v[134:135], v[106:107], v[106:107]
	v_pk_mul_f32 v[136:137], v[108:109], v[108:109]
	v_add_f32_e32 v130, v130, v131
	v_add_f32_e32 v132, v132, v133
	v_add_f32_e32 v134, v134, v135
	v_add_f32_e32 v136, v136, v137
	v_add_f32_e32 v130, v130, v132
	v_add_f32_e32 v134, v134, v136
	v_add_f32_e32 v140, v130, v134
	v_pk_add_f32 v[102:103], v[102:103], v[200:201]
	v_pk_add_f32 v[104:105], v[104:105], v[202:203]
	v_pk_add_f32 v[98:99], v[98:99], v[204:205]
	v_pk_add_f32 v[100:101], v[100:101], v[206:207]
	v_cvt_pk_bf16_f32 v200, v102, v103
	v_cvt_pk_bf16_f32 v201, v104, v105
	v_cvt_pk_bf16_f32 v202, v98, v99
	v_cvt_pk_bf16_f32 v203, v100, v101
	global_store_dwordx4 v[212:213], v[200:203], off offset:256
	v_pk_mul_f32 v[130:131], v[102:103], v[102:103]
	v_pk_mul_f32 v[132:133], v[104:105], v[104:105]
	v_pk_mul_f32 v[134:135], v[98:99], v[98:99]
	v_pk_mul_f32 v[136:137], v[100:101], v[100:101]
	v_add_f32_e32 v130, v130, v131
	v_add_f32_e32 v132, v132, v133
	v_add_f32_e32 v134, v134, v135
	v_add_f32_e32 v136, v136, v137
	v_add_f32_e32 v130, v130, v132
	v_add_f32_e32 v134, v134, v136
	v_add_f32_e32 v130, v130, v134
	v_add_f32_e32 v140, v140, v130
	ds_swizzle_b32 v141, v140 offset:swizzle(SWAP,16)
	s_waitcnt lgkmcnt(0)
; __device__ __forceinline__ float blo(unsigned u) { return __uint_as_float(u << 16); }
; __device__ __forceinline__ float bhi(unsigned u) { return __uint_as_float(u & 0xffff0000u); }
; __device__ __forceinline__ unsigned pk2(float lo, float hi) { pk_f32x2_t v = {lo, hi}; pk_bf16x2_t b = __builtin_convertvector(v, pk_bf16x2_t); return __builtin_bit_cast(unsigned, b); }
; template <int K> __device__ __forceinline__ float swz_f(float v) { return __uint_as_float(swz_u<K>(__float_as_uint(v))); }
;     __device__ __forceinline__ void operator()(const pg8::f32x4 (&acc)[2][2][4][2], const pg8::Unit& u, int wr, int wc, int fr, int fq) const {
;         const int row0 = u.pm * 256 + wr * 64 + fr, col0 = u.pn * 256 + wc * 32 + 8 * fq;
; #pragma unroll
;         for (int ai = 0; ai < 2; ++ai)
; #pragma unroll
;             for (int m = 0; m < 4; ++m) {
;                 const int row = row0 + ai * 128 + m * 16; const size_t off = (size_t)row * DM + col0; float sq = 0.f;
; #pragma unroll
;                 for (int bj = 0; bj < 2; ++bj) { const size_t o = off + bj * 128; f32x4 xa, xc;
;                     if (xin) { xa = *(const f32x4*)(xin + o); xc = *(const f32x4*)(xin + o + 4); }
;                     else { const u32x4 r4 = *(const u32x4*)(xin_b + o); xa[0] = blo(r4.x); xa[1] = bhi(r4.x); xa[2] = blo(r4.y); xa[3] = bhi(r4.y); xc[0] = blo(r4.z); xc[1] = bhi(r4.z); xc[2] = blo(r4.w); xc[3] = bhi(r4.w); }
;                     f32x4 va, vc;
;                     va[0] = xa[0] + acc[ai][bj][m][0][0]; va[1] = xa[1] + acc[ai][bj][m][0][1]; va[2] = xa[2] + acc[ai][bj][m][0][2]; va[3] = xa[3] + acc[ai][bj][m][0][3];
;                     vc[0] = xc[0] + acc[ai][bj][m][1][0]; vc[1] = xc[1] + acc[ai][bj][m][1][1]; vc[2] = xc[2] + acc[ai][bj][m][1][2]; vc[3] = xc[3] + acc[ai][bj][m][1][3];
;                     if (xout) { *(f32x4*)(xout + o) = va; *(f32x4*)(xout + o + 4) = vc; }
;                     if (xb) { u32x4 w; w.x = pk2(va[0], va[1]); w.y = pk2(va[2], va[3]); w.z = pk2(vc[0], vc[1]); w.w = pk2(vc[2], vc[3]); *(u32x4*)(xb + o) = w; }
;                     sq += ((va[0] * va[0] + va[1] * va[1]) + (va[2] * va[2] + va[3] * va[3])) + ((vc[0] * vc[0] + vc[1] * vc[1]) + (vc[2] * vc[2] + vc[3] * vc[3])); }
;                 if (ss) { sq += swz_f<16>(sq); sq = sum32(sq); if (fq == 0) atomicAdd(ss + row, sq); }
	v_add_f32_e32 v140, v140, v141
	v_mov_b32_e32 v141, v140
	s_nop 1
	v_permlane32_swap_b32_e32 v140, v141
	s_and_saveexec_b64 s[44:45], s[36:37]
	v_add_f32_e32 v140, v140, v141
	global_atomic_add_f32 v[230:231], v140, off offset:64
	s_or_b64 exec, exec, s[44:45]
	v_pk_add_f32 v[94:95], v[94:95], v[218:219]
	v_pk_add_f32 v[96:97], v[96:97], v[220:221]
	v_pk_add_f32 v[90:91], v[90:91], v[222:223]
	v_pk_add_f32 v[92:93], v[92:93], v[224:225]
	s_mov_b32 s98, 0x10000
	v_lshl_add_u64 v[212:213], v[228:229], 0, s[98:99]
	v_cvt_pk_bf16_f32 v218, v94, v95
	v_cvt_pk_bf16_f32 v219, v96, v97
	v_cvt_pk_bf16_f32 v220, v90, v91
	v_cvt_pk_bf16_f32 v221, v92, v93
	global_store_dwordx4 v[212:213], v[218:221], off
	v_pk_mul_f32 v[130:131], v[94:95], v[94:95]
	v_pk_mul_f32 v[132:133], v[96:97], v[96:97]
	v_pk_mul_f32 v[134:135], v[90:91], v[90:91]
	v_pk_mul_f32 v[136:137], v[92:93], v[92:93]
	v_add_f32_e32 v130, v130, v131
	v_add_f32_e32 v132, v132, v133
	v_add_f32_e32 v134, v134, v135
	v_add_f32_e32 v136, v136, v137
	v_add_f32_e32 v130, v130, v132
	v_add_f32_e32 v134, v134, v136
	v_add_f32_e32 v140, v130, v134
	v_pk_add_f32 v[86:87], v[86:87], v[160:161]
	v_pk_add_f32 v[88:89], v[88:89], v[162:163]
	v_pk_add_f32 v[82:83], v[82:83], v[164:165]
	v_pk_add_f32 v[84:85], v[84:85], v[166:167]
	v_cvt_pk_bf16_f32 v160, v86, v87
	v_cvt_pk_bf16_f32 v161, v88, v89
	v_cvt_pk_bf16_f32 v162, v82, v83
	v_cvt_pk_bf16_f32 v163, v84, v85
	global_store_dwordx4 v[212:213], v[160:163], off offset:256
	v_pk_mul_f32 v[130:131], v[86:87], v[86:87]
	v_pk_mul_f32 v[132:133], v[88:89], v[88:89]
	v_pk_mul_f32 v[134:135], v[82:83], v[82:83]
	v_pk_mul_f32 v[136:137], v[84:85], v[84:85]
	v_add_f32_e32 v130, v130, v131
	v_add_f32_e32 v132, v132, v133
	v_add_f32_e32 v134, v134, v135
	v_add_f32_e32 v136, v136, v137
	v_add_f32_e32 v130, v130, v132
	v_add_f32_e32 v134, v134, v136
	v_add_f32_e32 v130, v130, v134
	v_add_f32_e32 v140, v140, v130
	ds_swizzle_b32 v141, v140 offset:swizzle(SWAP,16)
	s_waitcnt lgkmcnt(0)
	v_add_f32_e32 v140, v140, v141
	v_mov_b32_e32 v141, v140
	s_nop 1
	v_permlane32_swap_b32_e32 v140, v141
	s_and_saveexec_b64 s[44:45], s[36:37]
	v_add_f32_e32 v140, v140, v141
	global_atomic_add_f32 v[230:231], v140, off offset:128
	s_or_b64 exec, exec, s[44:45]
	s_and_b64 vcc, exec, s[14:15]
	s_cbranch_vccnz .Lo_f32_ld_1
	s_mov_b32 s98, 0x18000
	v_lshl_add_u64 v[212:213], v[228:229], 0, s[98:99]
	global_load_dwordx4 v[180:183], v[212:213], off
	global_load_dwordx4 v[188:191], v[212:213], off offset:256
	s_mov_b32 s98, 0x40000
	v_lshl_add_u64 v[212:213], v[228:229], 0, s[98:99]
	global_load_dwordx4 v[196:199], v[212:213], off
	global_load_dwordx4 v[204:207], v[212:213], off offset:256
	s_mov_b32 s98, 0x48000
	v_lshl_add_u64 v[212:213], v[228:229], 0, s[98:99]
	global_load_dwordx4 v[222:225], v[212:213], off
	global_load_dwordx4 v[164:167], v[212:213], off offset:256
	s_branch .Lo_ld_done_1
.Lo_f32_ld_1:
	s_mov_b32 s98, 0x30000
	v_lshl_add_u64 v[212:213], v[226:227], 0, s[98:99]
	global_load_dwordx4 v[176:179], v[212:213], off
	global_load_dwordx4 v[180:183], v[212:213], off offset:16
	global_load_dwordx4 v[184:187], v[212:213], off offset:512
	global_load_dwordx4 v[188:191], v[212:213], off offset:528
	s_mov_b32 s98, 0x80000
	v_lshl_add_u64 v[212:213], v[226:227], 0, s[98:99]
	global_load_dwordx4 v[192:195], v[212:213], off
	global_load_dwordx4 v[196:199], v[212:213], off offset:16
	global_load_dwordx4 v[200:203], v[212:213], off offset:512
	global_load_dwordx4 v[204:207], v[212:213], off offset:528
	s_mov_b32 s98, 0x90000
	v_lshl_add_u64 v[212:213], v[226:227], 0, s[98:99]
	global_load_dwordx4 v[218:221], v[212:213], off
	global_load_dwordx4 v[222:225], v[212:213], off offset:16
	global_load_dwordx4 v[160:163], v[212:213], off offset:512
	global_load_dwordx4 v[164:167], v[212:213], off offset:528

; __device__ __forceinline__ float blo(unsigned u) { return __uint_as_float(u << 16); }
; __device__ __forceinline__ float bhi(unsigned u) { return __uint_as_float(u & 0xffff0000u); }
; __device__ __forceinline__ unsigned pk2(float lo, float hi) { pk_f32x2_t v = {lo, hi}; pk_bf16x2_t b = __builtin_convertvector(v, pk_bf16x2_t); return __builtin_bit_cast(unsigned, b); }
; template <int K> __device__ __forceinline__ float swz_f(float v) { return __uint_as_float(swz_u<K>(__float_as_uint(v))); }
;     __device__ __forceinline__ void operator()(const pg8::f32x4 (&acc)[2][2][4][2], const pg8::Unit& u, int wr, int wc, int fr, int fq) const {
;         const int row0 = u.pm * 256 + wr * 64 + fr, col0 = u.pn * 256 + wc * 32 + 8 * fq;
; #pragma unroll
;         for (int ai = 0; ai < 2; ++ai)
; #pragma unroll
;             for (int m = 0; m < 4; ++m) {
;                 const int row = row0 + ai * 128 + m * 16; const size_t off = (size_t)row * DM + col0; float sq = 0.f;
; #pragma unroll
;                 for (int bj = 0; bj < 2; ++bj) { const size_t o = off + bj * 128; f32x4 xa, xc;
;                     if (xin) { xa = *(const f32x4*)(xin + o); xc = *(const f32x4*)(xin + o + 4); }
;                     else { const u32x4 r4 = *(const u32x4*)(xin_b + o); xa[0] = blo(r4.x); xa[1] = bhi(r4.x); xa[2] = blo(r4.y); xa[3] = bhi(r4.y); xc[0] = blo(r4.z); xc[1] = bhi(r4.z); xc[2] = blo(r4.w); xc[3] = bhi(r4.w); }
;                     f32x4 va, vc;
;                     va[0] = xa[0] + acc[ai][bj][m][0][0]; va[1] = xa[1] + acc[ai][bj][m][0][1]; va[2] = xa[2] + acc[ai][bj][m][0][2]; va[3] = xa[3] + acc[ai][bj][m][0][3];
;                     vc[0] = xc[0] + acc[ai][bj][m][1][0]; vc[1] = xc[1] + acc[ai][bj][m][1][1]; vc[2] = xc[2] + acc[ai][bj][m][1][2]; vc[3] = xc[3] + acc[ai][bj][m][1][3];
;                     if (xout) { *(f32x4*)(xout + o) = va; *(f32x4*)(xout + o + 4) = vc; }
;                     if (xb) { u32x4 w; w.x = pk2(va[0], va[1]); w.y = pk2(va[2], va[3]); w.z = pk2(vc[0], vc[1]); w.w = pk2(vc[2], vc[3]); *(u32x4*)(xb + o) = w; }
;                     sq += ((va[0] * va[0] + va[1] * va[1]) + (va[2] * va[2] + va[3] * va[3])) + ((vc[0] * vc[0] + vc[1] * vc[1]) + (vc[2] * vc[2] + vc[3] * vc[3])); }
;                 if (ss) { sq += swz_f<16>(sq); sq = sum32(sq); if (fq == 0) atomicAdd(ss + row, sq); }
.Lo_common_1:
	v_pk_add_f32 v[78:79], v[78:79], v[176:177]
	v_pk_add_f32 v[80:81], v[80:81], v[178:179]
	v_pk_add_f32 v[74:75], v[74:75], v[180:181]
	v_pk_add_f32 v[76:77], v[76:77], v[182:183]
	s_mov_b32 s98, 0x18000
	v_lshl_add_u64 v[212:213], v[228:229], 0, s[98:99]
	v_cvt_pk_bf16_f32 v176, v78, v79
	v_cvt_pk_bf16_f32 v177, v80, v81
	v_cvt_pk_bf16_f32 v178, v74, v75
	v_cvt_pk_bf16_f32 v179, v76, v77
	global_store_dwordx4 v[212:213], v[176:179], off
	v_pk_mul_f32 v[130:131], v[78:79], v[78:79]
	v_pk_mul_f32 v[132:133], v[80:81], v[80:81]
	v_pk_mul_f32 v[134:135], v[74:75], v[74:75]
	v_pk_mul_f32 v[136:137], v[76:77], v[76:77]
	v_add_f32_e32 v130, v130, v131
	v_add_f32_e32 v132, v132, v133
	v_add_f32_e32 v134, v134, v135
	v_add_f32_e32 v136, v136, v137
	v_add_f32_e32 v130, v130, v132
	v_add_f32_e32 v134, v134, v136
	v_add_f32_e32 v140, v130, v134
	v_pk_add_f32 v[70:71], v[70:71], v[184:185]
	v_pk_add_f32 v[72:73], v[72:73], v[186:187]
	v_pk_add_f32 v[66:67], v[66:67], v[188:189]
	v_pk_add_f32 v[68:69], v[68:69], v[190:191]
	v_cvt_pk_bf16_f32 v184, v70, v71
	v_cvt_pk_bf16_f32 v185, v72, v73
	v_cvt_pk_bf16_f32 v186, v66, v67
	v_cvt_pk_bf16_f32 v187, v68, v69
	global_store_dwordx4 v[212:213], v[184:187], off offset:256
	v_pk_mul_f32 v[130:131], v[70:71], v[70:71]
	v_pk_mul_f32 v[132:133], v[72:73], v[72:73]
	v_pk_mul_f32 v[134:135], v[66:67], v[66:67]
	v_pk_mul_f32 v[136:137], v[68:69], v[68:69]
	v_add_f32_e32 v130, v130, v131
	v_add_f32_e32 v132, v132, v133
	v_add_f32_e32 v134, v134, v135
	v_add_f32_e32 v136, v136, v137
	v_add_f32_e32 v130, v130, v132
	v_add_f32_e32 v134, v134, v136
	v_add_f32_e32 v130, v130, v134
	v_add_f32_e32 v140, v140, v130
	ds_swizzle_b32 v141, v140 offset:swizzle(SWAP,16)
	s_waitcnt lgkmcnt(0)
	v_add_f32_e32 v140, v140, v141
	v_mov_b32_e32 v141, v140
	s_nop 1
	v_permlane32_swap_b32_e32 v140, v141
	s_and_saveexec_b64 s[44:45], s[36:37]
	v_add_f32_e32 v140, v140, v141
	global_atomic_add_f32 v[230:231], v140, off offset:192
	s_or_b64 exec, exec, s[44:45]
	v_pk_add_f32 v[62:63], v[62:63], v[192:193]
	v_pk_add_f32 v[64:65], v[64:65], v[194:195]
	v_pk_add_f32 v[58:59], v[58:59], v[196:197]
	v_pk_add_f32 v[60:61], v[60:61], v[198:199]
	s_mov_b32 s98, 0x40000
	v_lshl_add_u64 v[212:213], v[228:229], 0, s[98:99]
	v_cvt_pk_bf16_f32 v192, v62, v63
	v_cvt_pk_bf16_f32 v193, v64, v65
	v_cvt_pk_bf16_f32 v194, v58, v59
	v_cvt_pk_bf16_f32 v195, v60, v61
	global_store_dwordx4 v[212:213], v[192:195], off
	v_pk_mul_f32 v[130:131], v[62:63], v[62:63]
	v_pk_mul_f32 v[132:133], v[64:65], v[64:65]
	v_pk_mul_f32 v[134:135], v[58:59], v[58:59]
	v_pk_mul_f32 v[136:137], v[60:61], v[60:61]
	v_add_f32_e32 v130, v130, v131
	v_add_f32_e32 v132, v132, v133
	v_add_f32_e32 v134, v134, v135
	v_add_f32_e32 v136, v136, v137
	v_add_f32_e32 v130, v130, v132
	v_add_f32_e32 v134, v134, v136
	v_add_f32_e32 v140, v130, v134
	v_pk_add_f32 v[54:55], v[54:55], v[200:201]
	v_pk_add_f32 v[56:57], v[56:57], v[202:203]
	v_pk_add_f32 v[50:51], v[50:51], v[204:205]
	v_pk_add_f32 v[52:53], v[52:53], v[206:207]
	v_cvt_pk_bf16_f32 v200, v54, v55
	v_cvt_pk_bf16_f32 v201, v56, v57
	v_cvt_pk_bf16_f32 v202, v50, v51
	v_cvt_pk_bf16_f32 v203, v52, v53
	global_store_dwordx4 v[212:213], v[200:203], off offset:256
	v_pk_mul_f32 v[130:131], v[54:55], v[54:55]
	v_pk_mul_f32 v[132:133], v[56:57], v[56:57]
	v_pk_mul_f32 v[134:135], v[50:51], v[50:51]
	v_pk_mul_f32 v[136:137], v[52:53], v[52:53]
	v_add_f32_e32 v130, v130, v131
	v_add_f32_e32 v132, v132, v133
	v_add_f32_e32 v134, v134, v135
	v_add_f32_e32 v136, v136, v137
	v_add_f32_e32 v130, v130, v132
	v_add_f32_e32 v134, v134, v136
	v_add_f32_e32 v130, v130, v134
	v_add_f32_e32 v140, v140, v130
	ds_swizzle_b32 v141, v140 offset:swizzle(SWAP,16)
	s_waitcnt lgkmcnt(0)
	v_add_f32_e32 v140, v140, v141
	v_mov_b32_e32 v141, v140
	s_nop 1
	v_permlane32_swap_b32_e32 v140, v141
	s_and_saveexec_b64 s[44:45], s[36:37]
	v_add_f32_e32 v140, v140, v141
	global_atomic_add_f32 v[230:231], v140, off offset:512
	s_or_b64 exec, exec, s[44:45]
	v_pk_add_f32 v[46:47], v[46:47], v[218:219]
	v_pk_add_f32 v[48:49], v[48:49], v[220:221]
	v_pk_add_f32 v[42:43], v[42:43], v[222:223]
	v_pk_add_f32 v[44:45], v[44:45], v[224:225]
	s_mov_b32 s98, 0x48000
	v_lshl_add_u64 v[212:213], v[228:229], 0, s[98:99]
	v_cvt_pk_bf16_f32 v218, v46, v47
	v_cvt_pk_bf16_f32 v219, v48, v49
	v_cvt_pk_bf16_f32 v220, v42, v43
	v_cvt_pk_bf16_f32 v221, v44, v45
	global_store_dwordx4 v[212:213], v[218:221], off
	v_pk_mul_f32 v[130:131], v[46:47], v[46:47]
	v_pk_mul_f32 v[132:133], v[48:49], v[48:49]
	v_pk_mul_f32 v[134:135], v[42:43], v[42:43]
	v_pk_mul_f32 v[136:137], v[44:45], v[44:45]
	v_add_f32_e32 v130, v130, v131
	v_add_f32_e32 v132, v132, v133
	v_add_f32_e32 v134, v134, v135
	v_add_f32_e32 v136, v136, v137
	v_add_f32_e32 v130, v130, v132
	v_add_f32_e32 v134, v134, v136
	v_add_f32_e32 v140, v130, v134
	v_pk_add_f32 v[38:39], v[38:39], v[160:161]
	v_pk_add_f32 v[40:41], v[40:41], v[162:163]
	v_pk_add_f32 v[34:35], v[34:35], v[164:165]
	v_pk_add_f32 v[36:37], v[36:37], v[166:167]
	v_cvt_pk_bf16_f32 v160, v38, v39
	v_cvt_pk_bf16_f32 v161, v40, v41
	v_cvt_pk_bf16_f32 v162, v34, v35
	v_cvt_pk_bf16_f32 v163, v36, v37
	global_store_dwordx4 v[212:213], v[160:163], off offset:256
	v_pk_mul_f32 v[130:131], v[38:39], v[38:39]
	v_pk_mul_f32 v[132:133], v[40:41], v[40:41]
	v_pk_mul_f32 v[134:135], v[34:35], v[34:35]
	v_pk_mul_f32 v[136:137], v[36:37], v[36:37]
	v_add_f32_e32 v130, v130, v131
	v_add_f32_e32 v132, v132, v133
	v_add_f32_e32 v134, v134, v135
	v_add_f32_e32 v136, v136, v137
	v_add_f32_e32 v130, v130, v132
	v_add_f32_e32 v134, v134, v136
	v_add_f32_e32 v130, v130, v134
	v_add_f32_e32 v140, v140, v130
	ds_swizzle_b32 v141, v140 offset:swizzle(SWAP,16)
	s_waitcnt lgkmcnt(0)
	v_add_f32_e32 v140, v140, v141
	v_mov_b32_e32 v141, v140
	s_nop 1
	v_permlane32_swap_b32_e32 v140, v141
	s_and_saveexec_b64 s[44:45], s[36:37]
	v_add_f32_e32 v140, v140, v141
	global_atomic_add_f32 v[230:231], v140, off offset:576
	s_or_b64 exec, exec, s[44:45]
	s_and_b64 vcc, exec, s[14:15]
	s_cbranch_vccnz .Lo_f32_ld_2
	s_mov_b32 s98, 0x50000
	v_lshl_add_u64 v[212:213], v[228:229], 0, s[98:99]
	global_load_dwordx4 v[180:183], v[212:213], off
	global_load_dwordx4 v[188:191], v[212:213], off offset:256
	s_mov_b32 s98, 0x58000
	v_lshl_add_u64 v[212:213], v[228:229], 0, s[98:99]
	global_load_dwordx4 v[196:199], v[212:213], off
	global_load_dwordx4 v[204:207], v[212:213], off offset:256
	s_branch .Lo_ld_done_2
; __device__ __forceinline__ float blo(unsigned u) { return __uint_as_float(u << 16); }
; __device__ __forceinline__ float bhi(unsigned u) { return __uint_as_float(u & 0xffff0000u); }
; __device__ __forceinline__ unsigned pk2(float lo, float hi) { pk_f32x2_t v = {lo, hi}; pk_bf16x2_t b = __builtin_convertvector(v, pk_bf16x2_t); return __builtin_bit_cast(unsigned, b); }
; template <int K> __device__ __forceinline__ float swz_f(float v) { return __uint_as_float(swz_u<K>(__float_as_uint(v))); }
;     __device__ __forceinline__ void operator()(const pg8::f32x4 (&acc)[2][2][4][2], const pg8::Unit& u, int wr, int wc, int fr, int fq) const {
;         const int row0 = u.pm * 256 + wr * 64 + fr, col0 = u.pn * 256 + wc * 32 + 8 * fq;
; #pragma unroll
;         for (int ai = 0; ai < 2; ++ai)
; #pragma unroll
;             for (int m = 0; m < 4; ++m) {
;                 const int row = row0 + ai * 128 + m * 16; const size_t off = (size_t)row * DM + col0; float sq = 0.f;
; #pragma unroll
;                 for (int bj = 0; bj < 2; ++bj) { const size_t o = off + bj * 128; f32x4 xa, xc;
;                     if (xin) { xa = *(const f32x4*)(xin + o); xc = *(const f32x4*)(xin + o + 4); }
;                     else { const u32x4 r4 = *(const u32x4*)(xin_b + o); xa[0] = blo(r4.x); xa[1] = bhi(r4.x); xa[2] = blo(r4.y); xa[3] = bhi(r4.y); xc[0] = blo(r4.z); xc[1] = bhi(r4.z); xc[2] = blo(r4.w); xc[3] = bhi(r4.w); }
;                     f32x4 va, vc;
;                     va[0] = xa[0] + acc[ai][bj][m][0][0]; va[1] = xa[1] + acc[ai][bj][m][0][1]; va[2] = xa[2] + acc[ai][bj][m][0][2]; va[3] = xa[3] + acc[ai][bj][m][0][3];
;                     vc[0] = xc[0] + acc[ai][bj][m][1][0]; vc[1] = xc[1] + acc[ai][bj][m][1][1]; vc[2] = xc[2] + acc[ai][bj][m][1][2]; vc[3] = xc[3] + acc[ai][bj][m][1][3];
;                     if (xout) { *(f32x4*)(xout + o) = va; *(f32x4*)(xout + o + 4) = vc; }
;                     if (xb) { u32x4 w; w.x = pk2(va[0], va[1]); w.y = pk2(va[2], va[3]); w.z = pk2(vc[0], vc[1]); w.w = pk2(vc[2], vc[3]); *(u32x4*)(xb + o) = w; }
;                     sq += ((va[0] * va[0] + va[1] * va[1]) + (va[2] * va[2] + va[3] * va[3])) + ((vc[0] * vc[0] + vc[1] * vc[1]) + (vc[2] * vc[2] + vc[3] * vc[3])); }
;                 if (ss) { sq += swz_f<16>(sq); sq = sum32(sq); if (fq == 0) atomicAdd(ss + row, sq); }
.Lo_f32_ld_2:
	s_mov_b32 s98, 0xa0000
	v_lshl_add_u64 v[212:213], v[226:227], 0, s[98:99]
	global_load_dwordx4 v[176:179], v[212:213], off
	global_load_dwordx4 v[180:183], v[212:213], off offset:16
	global_load_dwordx4 v[184:187], v[212:213], off offset:512
	global_load_dwordx4 v[188:191], v[212:213], off offset:528
	s_mov_b32 s98, 0xb0000
	v_lshl_add_u64 v[212:213], v[226:227], 0, s[98:99]
	global_load_dwordx4 v[192:195], v[212:213], off
	global_load_dwordx4 v[196:199], v[212:213], off offset:16
	global_load_dwordx4 v[200:203], v[212:213], off offset:512
	global_load_dwordx4 v[204:207], v[212:213], off offset:528
.Lo_ld_done_2:
	s_waitcnt vmcnt(0)
	s_and_b64 vcc, exec, s[14:15]
	s_cbranch_vccnz .Lo_common_2
	v_lshlrev_b32_e32 v176, 16, v180
	v_and_b32_e32 v177, 0xffff0000, v180
	v_lshlrev_b32_e32 v178, 16, v181
	v_and_b32_e32 v179, 0xffff0000, v181
	v_lshlrev_b32_e32 v180, 16, v182
	v_and_b32_e32 v181, 0xffff0000, v182
	v_lshlrev_b32_e32 v182, 16, v183
	v_and_b32_e32 v183, 0xffff0000, v183
	v_lshlrev_b32_e32 v184, 16, v188
	v_and_b32_e32 v185, 0xffff0000, v188
	v_lshlrev_b32_e32 v186, 16, v189
	v_and_b32_e32 v187, 0xffff0000, v189
	v_lshlrev_b32_e32 v188, 16, v190
	v_and_b32_e32 v189, 0xffff0000, v190
	v_lshlrev_b32_e32 v190, 16, v191
	v_and_b32_e32 v191, 0xffff0000, v191
	v_lshlrev_b32_e32 v192, 16, v196
	v_and_b32_e32 v193, 0xffff0000, v196
	v_lshlrev_b32_e32 v194, 16, v197
	v_and_b32_e32 v195, 0xffff0000, v197
	v_lshlrev_b32_e32 v196, 16, v198
	v_and_b32_e32 v197, 0xffff0000, v198
	v_lshlrev_b32_e32 v198, 16, v199
	v_and_b32_e32 v199, 0xffff0000, v199
	v_lshlrev_b32_e32 v200, 16, v204
	v_and_b32_e32 v201, 0xffff0000, v204
	v_lshlrev_b32_e32 v202, 16, v205
	v_and_b32_e32 v203, 0xffff0000, v205
	v_lshlrev_b32_e32 v204, 16, v206
	v_and_b32_e32 v205, 0xffff0000, v206
	v_lshlrev_b32_e32 v206, 16, v207
	v_and_b32_e32 v207, 0xffff0000, v207
.Lo_common_2:
	v_pk_add_f32 v[30:31], v[30:31], v[176:177]
	v_pk_add_f32 v[32:33], v[32:33], v[178:179]
	v_pk_add_f32 v[26:27], v[26:27], v[180:181]
	v_pk_add_f32 v[28:29], v[28:29], v[182:183]
	s_mov_b32 s98, 0x50000
	v_lshl_add_u64 v[212:213], v[228:229], 0, s[98:99]
	v_cvt_pk_bf16_f32 v176, v30, v31
	v_cvt_pk_bf16_f32 v177, v32, v33
	v_cvt_pk_bf16_f32 v178, v26, v27
	v_cvt_pk_bf16_f32 v179, v28, v29
	global_store_dwordx4 v[212:213], v[176:179], off
	v_pk_mul_f32 v[130:131], v[30:31], v[30:31]
	v_pk_mul_f32 v[132:133], v[32:33], v[32:33]
	v_pk_mul_f32 v[134:135], v[26:27], v[26:27]
	v_pk_mul_f32 v[136:137], v[28:29], v[28:29]
	v_add_f32_e32 v130, v130, v131
	v_add_f32_e32 v132, v132, v133
	v_add_f32_e32 v134, v134, v135
	v_add_f32_e32 v136, v136, v137
	v_add_f32_e32 v130, v130, v132
	v_add_f32_e32 v134, v134, v136
	v_add_f32_e32 v140, v130, v134
	v_pk_add_f32 v[22:23], v[22:23], v[184:185]
	v_pk_add_f32 v[24:25], v[24:25], v[186:187]
	v_pk_add_f32 v[18:19], v[18:19], v[188:189]
	v_pk_add_f32 v[20:21], v[20:21], v[190:191]
	v_cvt_pk_bf16_f32 v184, v22, v23
	v_cvt_pk_bf16_f32 v185, v24, v25
	v_cvt_pk_bf16_f32 v186, v18, v19
	v_cvt_pk_bf16_f32 v187, v20, v21
	global_store_dwordx4 v[212:213], v[184:187], off offset:256
	v_pk_mul_f32 v[130:131], v[22:23], v[22:23]
	v_pk_mul_f32 v[132:133], v[24:25], v[24:25]
	v_pk_mul_f32 v[134:135], v[18:19], v[18:19]
	v_pk_mul_f32 v[136:137], v[20:21], v[20:21]
	v_add_f32_e32 v130, v130, v131
	v_add_f32_e32 v132, v132, v133
	v_add_f32_e32 v134, v134, v135
	v_add_f32_e32 v136, v136, v137
	v_add_f32_e32 v130, v130, v132
	v_add_f32_e32 v134, v134, v136
	v_add_f32_e32 v130, v130, v134
	v_add_f32_e32 v140, v140, v130
	ds_swizzle_b32 v141, v140 offset:swizzle(SWAP,16)
	s_waitcnt lgkmcnt(0)
	v_add_f32_e32 v140, v140, v141
	v_mov_b32_e32 v141, v140
	s_nop 1
	v_permlane32_swap_b32_e32 v140, v141
	s_and_saveexec_b64 s[44:45], s[36:37]
	v_add_f32_e32 v140, v140, v141
	global_atomic_add_f32 v[230:231], v140, off offset:640
	s_or_b64 exec, exec, s[44:45]
	v_pk_add_f32 v[14:15], v[14:15], v[192:193]
	v_pk_add_f32 v[16:17], v[16:17], v[194:195]
	v_pk_add_f32 v[10:11], v[10:11], v[196:197]
	v_pk_add_f32 v[12:13], v[12:13], v[198:199]
	s_mov_b32 s98, 0x58000
	v_lshl_add_u64 v[212:213], v[228:229], 0, s[98:99]
	v_cvt_pk_bf16_f32 v192, v14, v15
	v_cvt_pk_bf16_f32 v193, v16, v17
	v_cvt_pk_bf16_f32 v194, v10, v11
	v_cvt_pk_bf16_f32 v195, v12, v13
	global_store_dwordx4 v[212:213], v[192:195], off
	v_pk_mul_f32 v[130:131], v[14:15], v[14:15]
	v_pk_mul_f32 v[132:133], v[16:17], v[16:17]
	v_pk_mul_f32 v[134:135], v[10:11], v[10:11]
	v_pk_mul_f32 v[136:137], v[12:13], v[12:13]
	v_add_f32_e32 v130, v130, v131
	v_add_f32_e32 v132, v132, v133
	v_add_f32_e32 v134, v134, v135
	v_add_f32_e32 v136, v136, v137
	v_add_f32_e32 v130, v130, v132
	v_add_f32_e32 v134, v134, v136
	v_add_f32_e32 v140, v130, v134
	v_pk_add_f32 v[6:7], v[6:7], v[200:201]
	v_pk_add_f32 v[8:9], v[8:9], v[202:203]
	v_pk_add_f32 v[2:3], v[2:3], v[204:205]
	v_pk_add_f32 v[4:5], v[4:5], v[206:207]
	v_cvt_pk_bf16_f32 v200, v6, v7
	v_cvt_pk_bf16_f32 v201, v8, v9
	v_cvt_pk_bf16_f32 v202, v2, v3
	v_cvt_pk_bf16_f32 v203, v4, v5
	global_store_dwordx4 v[212:213], v[200:203], off offset:256
	v_pk_mul_f32 v[130:131], v[6:7], v[6:7]
	v_pk_mul_f32 v[132:133], v[8:9], v[8:9]
	v_pk_mul_f32 v[134:135], v[2:3], v[2:3]
	v_pk_mul_f32 v[136:137], v[4:5], v[4:5]
	v_add_f32_e32 v130, v130, v131
	v_add_f32_e32 v132, v132, v133
	v_add_f32_e32 v134, v134, v135
	v_add_f32_e32 v136, v136, v137
	v_add_f32_e32 v130, v130, v132
	v_add_f32_e32 v134, v134, v136
	v_add_f32_e32 v130, v130, v134
	v_add_f32_e32 v140, v140, v130
	ds_swizzle_b32 v141, v140 offset:swizzle(SWAP,16)
	s_waitcnt lgkmcnt(0)
	v_add_f32_e32 v140, v140, v141
	v_mov_b32_e32 v141, v140
	s_nop 1
	v_permlane32_swap_b32_e32 v140, v141
	s_and_saveexec_b64 s[44:45], s[36:37]
	v_add_f32_e32 v140, v140, v141
	global_atomic_add_f32 v[230:231], v140, off offset:704
	s_or_b64 exec, exec, s[44:45]
	s_andn2_b64 vcc, exec, s[40:41]
	s_mov_b64 s[40:41], -1
	s_cbranch_vccnz .LBB0_1371
	s_andn2_b64 vcc, exec, s[6:7]
	s_cbranch_vccnz .LBB0_1370
	s_barrier
	s_branch .LBB0_1370

; #define PG8_STAGE(bufoff, gbase, voff) do { _Pragma("unroll") for (int _i = 0; _i < 2; ++_i) \
;         __builtin_amdgcn_global_load_lds((const unsigned*)((const char*)(gbase) + (voff)[_i]), (PG8_LAS unsigned*)(lds + (bufoff) + ldsw + _i * 8192), 16, 0, 0); } while (0)
; #define PG8_LDA(dst, b, h) do { _Pragma("unroll") for (int m = 0; m < 4; ++m) _Pragma("unroll") for (int k = 0; k < 2; ++k) dst[m][k] = *(const PG8_LAS bf16x8*)(lds + PG8_SA(b, h) + aoff + m * 2048 + k * 1024); } while (0)
; #define PG8_LDB(dst, b, h) do { _Pragma("unroll") for (int n = 0; n < 2; ++n) _Pragma("unroll") for (int k = 0; k < 2; ++k) dst[n][k] = *(const PG8_LAS bf16x8*)(lds + PG8_SB(b, h) + boff + n * 2048 + k * 1024); } while (0)
; #define PG8_MMA(ai, bj, At, Bt) do { __builtin_amdgcn_s_setprio(1); _Pragma("unroll") for (int m = 0; m < 4; ++m) _Pragma("unroll") for (int n = 0; n < 2; ++n) _Pragma("unroll") for (int k = 0; k < 2; ++k) \
;         acc[ai][bj][m][n] = __builtin_amdgcn_mfma_f32_16x16x32_bf16(Bt[n][k], At[m][k], acc[ai][bj][m][n], 0, 0, 0); __builtin_amdgcn_s_setprio(0); } while (0)
; #define PG8_WAIT_V(n) asm volatile("s_waitcnt vmcnt(" #n ")" ::: "memory")
; #define PG8_WAIT_L(n) asm volatile("s_waitcnt lgkmcnt(" #n ")" ::: "memory")
; #define PG8_BAR __builtin_amdgcn_s_barrier()
; #define PG8_SCHED __builtin_amdgcn_sched_barrier(0)
; template <class Epi, class Sched, bool ALIGN_EPI = false, bool SP2 = false>
; __device__ __forceinline__ void gemm_phase(PG8_LAS unsigned char* lds, const Gemm g, const Sched& S, const Epi& E) {
;     ...
;             PG8_LDB(B0, 0, 0); PG8_LDB(B1, 0, 1); PG8_SCHED; PG8_LDA(At, 0, 0); PG8_STAGE(PG8_SA(1, 1), a1 + hstep, voffA);
;             PG8_WAIT_V(8); PG8_WAIT_L(0); PG8_BAR; PG8_MMA(0, 0, At, B0); PG8_MMA(0, 1, At, B1); PG8_BAR; PG8_SCHED;
;             PG8_LDA(At, 0, 1); PG8_STAGE(PG8_SB(0, 0), b2, voffB); PG8_STAGE(PG8_SB(0, 1), b2 + hstep, voffB); PG8_STAGE(PG8_SA(0, 0), a2, voffA);
;             PG8_WAIT_V(8); PG8_WAIT_L(0); PG8_BAR; PG8_MMA(1, 0, At, B0); PG8_MMA(1, 1, At, B1); PG8_BAR; PG8_SCHED;
.LBB0_1604:
	s_add_u32 s24, s18, 0x100
	s_addc_u32 s25, s19, 0
	s_add_i32 s58, 0, 0x10000
	s_cmp_eq_u32 s57, 40
	s_cselect_b32 s41, s5, s25
	s_cselect_b32 s40, s4, s24
	v_add_u32_e32 v140, s58, v163
	s_cselect_b32 s27, s17, s56
	s_cselect_b32 s26, s16, s55
	s_add_i32 s59, 0, 0x14000
	ds_read_b128 v[152:155], v140
	ds_read_b128 v[156:159], v140 offset:1024
	ds_read_b128 v[166:169], v140 offset:2048
	ds_read_b128 v[170:173], v140 offset:3072
	v_add_u32_e32 v140, s59, v163
	ds_read_b128 v[174:177], v140
	ds_read_b128 v[178:181], v140 offset:1024
	ds_read_b128 v[182:185], v140 offset:2048
	ds_read_b128 v[186:189], v140 offset:3072
	v_lshl_add_u64 v[140:141], s[18:19], 0, v[136:137]
	s_add_i32 m0, s46, 0xc000
	ds_read_b128 v[190:193], v165
	ds_read_b128 v[194:197], v165 offset:1024
	ds_read_b128 v[198:201], v165 offset:2048
	ds_read_b128 v[202:205], v165 offset:3072
	ds_read_b128 v[220:223], v165 offset:4096
	ds_read_b128 v[224:227], v165 offset:5120
	ds_read_b128 v[228:231], v165 offset:6144
	ds_read_b128 v[232:235], v165 offset:7168
	global_load_lds_dwordx4 v[140:141], off
	v_lshl_add_u64 v[140:141], s[18:19], 0, v[150:151]
	s_add_i32 m0, s46, 0xe000
	s_nop 0
	global_load_lds_dwordx4 v[140:141], off
	s_waitcnt vmcnt(8)
	s_waitcnt lgkmcnt(0)
	s_barrier
	s_setprio 1
	s_waitcnt lgkmcnt(0)
	v_mfma_f32_16x16x32_bf16 v[126:129], v[152:155], v[190:193], v[126:129]
	v_mfma_f32_16x16x32_bf16 v[122:125], v[166:169], v[190:193], v[122:125]
	v_mfma_f32_16x16x32_bf16 v[110:113], v[152:155], v[198:201], v[110:113]
	v_mfma_f32_16x16x32_bf16 v[106:109], v[166:169], v[198:201], v[106:109]
	v_mfma_f32_16x16x32_bf16 v[94:97], v[152:155], v[220:223], v[94:97]
	v_mfma_f32_16x16x32_bf16 v[90:93], v[166:169], v[220:223], v[90:93]
	v_mfma_f32_16x16x32_bf16 v[78:81], v[152:155], v[228:231], v[78:81]
	v_mfma_f32_16x16x32_bf16 v[74:77], v[166:169], v[228:231], v[74:77]
	v_mfma_f32_16x16x32_bf16 v[126:129], v[156:159], v[194:197], v[126:129]
	v_mfma_f32_16x16x32_bf16 v[122:125], v[170:173], v[194:197], v[122:125]
	v_mfma_f32_16x16x32_bf16 v[110:113], v[156:159], v[202:205], v[110:113]
	v_mfma_f32_16x16x32_bf16 v[106:109], v[170:173], v[202:205], v[106:109]
	v_mfma_f32_16x16x32_bf16 v[94:97], v[156:159], v[224:227], v[94:97]
	v_mfma_f32_16x16x32_bf16 v[90:93], v[170:173], v[224:227], v[90:93]
	v_mfma_f32_16x16x32_bf16 v[78:81], v[156:159], v[232:235], v[78:81]
	v_mfma_f32_16x16x32_bf16 v[74:77], v[170:173], v[232:235], v[74:77]
	s_setprio 0
	s_setprio 1
	v_mfma_f32_16x16x32_bf16 v[118:121], v[174:177], v[190:193], v[118:121]
	v_mfma_f32_16x16x32_bf16 v[114:117], v[182:185], v[190:193], v[114:117]
	v_mfma_f32_16x16x32_bf16 v[102:105], v[174:177], v[198:201], v[102:105]
	v_mfma_f32_16x16x32_bf16 v[98:101], v[182:185], v[198:201], v[98:101]
	v_mfma_f32_16x16x32_bf16 v[86:89], v[174:177], v[220:223], v[86:89]
	v_mfma_f32_16x16x32_bf16 v[82:85], v[182:185], v[220:223], v[82:85]
	v_mfma_f32_16x16x32_bf16 v[70:73], v[174:177], v[228:231], v[70:73]
	v_mfma_f32_16x16x32_bf16 v[66:69], v[182:185], v[228:231], v[66:69]
	v_mfma_f32_16x16x32_bf16 v[118:121], v[178:181], v[194:197], v[118:121]
	v_mfma_f32_16x16x32_bf16 v[114:117], v[186:189], v[194:197], v[114:117]
	v_mfma_f32_16x16x32_bf16 v[102:105], v[178:181], v[202:205], v[102:105]
	v_mfma_f32_16x16x32_bf16 v[98:101], v[186:189], v[202:205], v[98:101]
	v_mfma_f32_16x16x32_bf16 v[86:89], v[178:181], v[224:227], v[86:89]
	v_mfma_f32_16x16x32_bf16 v[82:85], v[186:189], v[224:227], v[82:85]
	v_mfma_f32_16x16x32_bf16 v[70:73], v[178:181], v[232:235], v[70:73]
	v_mfma_f32_16x16x32_bf16 v[66:69], v[186:189], v[232:235], v[66:69]
	s_setprio 0
	s_barrier
	s_add_i32 s18, s58, s45
	v_lshl_add_u64 v[140:141], s[26:27], 0, v[0:1]
	s_mov_b32 m0, s18
	ds_read_b128 v[190:193], v165 offset:16384
	ds_read_b128 v[194:197], v165 offset:17408
	ds_read_b128 v[198:201], v165 offset:18432
	ds_read_b128 v[202:205], v165 offset:19456
	ds_read_b128 v[220:223], v165 offset:20480
	ds_read_b128 v[224:227], v165 offset:21504
	ds_read_b128 v[228:231], v165 offset:22528
	ds_read_b128 v[232:235], v165 offset:23552
	global_load_lds_dwordx4 v[140:141], off
	s_add_i32 m0, s18, 0x2000
	s_add_u32 s18, s26, 0xb0000
	v_lshl_add_u64 v[146:147], s[26:27], 0, v[130:131]
	s_addc_u32 s19, s27, 0
	s_add_i32 s58, s59, s45
	global_load_lds_dwordx4 v[146:147], off
	v_lshl_add_u64 v[160:161], s[18:19], 0, v[0:1]
	s_mov_b32 m0, s58
	v_lshl_add_u64 v[206:207], s[40:41], 0, v[132:133]
	global_load_lds_dwordx4 v[160:161], off
	v_lshl_add_u64 v[160:161], s[18:19], 0, v[130:131]
	s_add_i32 m0, s58, 0x2000
	s_nop 0
	global_load_lds_dwordx4 v[160:161], off
	v_lshl_add_u64 v[160:161], s[40:41], 0, v[134:135]
	s_mov_b32 m0, s46
	s_nop 0
	global_load_lds_dwordx4 v[160:161], off
	s_mov_b32 m0, s47
	s_nop 0
	global_load_lds_dwordx4 v[206:207], off
	s_waitcnt vmcnt(8)
	s_waitcnt lgkmcnt(0)
	s_barrier
; #define PG8_STAGE(bufoff, gbase, voff) do { _Pragma("unroll") for (int _i = 0; _i < 2; ++_i) \
;         __builtin_amdgcn_global_load_lds((const unsigned*)((const char*)(gbase) + (voff)[_i]), (PG8_LAS unsigned*)(lds + (bufoff) + ldsw + _i * 8192), 16, 0, 0); } while (0)
; #define PG8_LDA(dst, b, h) do { _Pragma("unroll") for (int m = 0; m < 4; ++m) _Pragma("unroll") for (int k = 0; k < 2; ++k) dst[m][k] = *(const PG8_LAS bf16x8*)(lds + PG8_SA(b, h) + aoff + m * 2048 + k * 1024); } while (0)
; #define PG8_LDB(dst, b, h) do { _Pragma("unroll") for (int n = 0; n < 2; ++n) _Pragma("unroll") for (int k = 0; k < 2; ++k) dst[n][k] = *(const PG8_LAS bf16x8*)(lds + PG8_SB(b, h) + boff + n * 2048 + k * 1024); } while (0)
; #define PG8_MMA(ai, bj, At, Bt) do { __builtin_amdgcn_s_setprio(1); _Pragma("unroll") for (int m = 0; m < 4; ++m) _Pragma("unroll") for (int n = 0; n < 2; ++n) _Pragma("unroll") for (int k = 0; k < 2; ++k) \
;         acc[ai][bj][m][n] = __builtin_amdgcn_mfma_f32_16x16x32_bf16(Bt[n][k], At[m][k], acc[ai][bj][m][n], 0, 0, 0); __builtin_amdgcn_s_setprio(0); } while (0)
; #define PG8_WAIT_V(n) asm volatile("s_waitcnt vmcnt(" #n ")" ::: "memory")
; #define PG8_WAIT_L(n) asm volatile("s_waitcnt lgkmcnt(" #n ")" ::: "memory")
; #define PG8_BAR __builtin_amdgcn_s_barrier()
; #define PG8_SCHED __builtin_amdgcn_sched_barrier(0)
; template <class Epi, class Sched, bool ALIGN_EPI = false, bool SP2 = false>
; __device__ __forceinline__ void gemm_phase(PG8_LAS unsigned char* lds, const Gemm g, const Sched& S, const Epi& E) {
;     ...
;             PG8_WAIT_V(8); PG8_WAIT_L(0); PG8_BAR; PG8_MMA(1, 0, At, B0); PG8_MMA(1, 1, At, B1); PG8_BAR; PG8_SCHED;
;             PG8_LDB(B0, 1, 0); PG8_LDB(B1, 1, 1); PG8_SCHED; PG8_LDA(At, 1, 0); PG8_STAGE(PG8_SA(0, 1), a2 + hstep, voffA);
;             PG8_WAIT_V(8); PG8_WAIT_L(0); PG8_BAR; PG8_MMA(0, 0, At, B0); PG8_MMA(0, 1, At, B1); PG8_BAR; PG8_SCHED;
	s_setprio 1
	s_waitcnt lgkmcnt(0)
	v_mfma_f32_16x16x32_bf16 v[62:65], v[152:155], v[190:193], v[62:65]
	v_mfma_f32_16x16x32_bf16 v[58:61], v[166:169], v[190:193], v[58:61]
	v_mfma_f32_16x16x32_bf16 v[46:49], v[152:155], v[198:201], v[46:49]
	v_mfma_f32_16x16x32_bf16 v[42:45], v[166:169], v[198:201], v[42:45]
	v_mfma_f32_16x16x32_bf16 v[30:33], v[152:155], v[220:223], v[30:33]
	v_mfma_f32_16x16x32_bf16 v[26:29], v[166:169], v[220:223], v[26:29]
	v_mfma_f32_16x16x32_bf16 v[14:17], v[152:155], v[228:231], v[14:17]
	v_mfma_f32_16x16x32_bf16 v[10:13], v[166:169], v[228:231], v[10:13]
	v_mfma_f32_16x16x32_bf16 v[62:65], v[156:159], v[194:197], v[62:65]
	v_mfma_f32_16x16x32_bf16 v[58:61], v[170:173], v[194:197], v[58:61]
	v_mfma_f32_16x16x32_bf16 v[46:49], v[156:159], v[202:205], v[46:49]
	v_mfma_f32_16x16x32_bf16 v[42:45], v[170:173], v[202:205], v[42:45]
	v_mfma_f32_16x16x32_bf16 v[30:33], v[156:159], v[224:227], v[30:33]
	v_mfma_f32_16x16x32_bf16 v[26:29], v[170:173], v[224:227], v[26:29]
	v_mfma_f32_16x16x32_bf16 v[14:17], v[156:159], v[232:235], v[14:17]
	v_mfma_f32_16x16x32_bf16 v[10:13], v[170:173], v[232:235], v[10:13]
	s_setprio 0
	s_setprio 1
	v_mfma_f32_16x16x32_bf16 v[54:57], v[174:177], v[190:193], v[54:57]
	v_mfma_f32_16x16x32_bf16 v[50:53], v[182:185], v[190:193], v[50:53]
	v_mfma_f32_16x16x32_bf16 v[38:41], v[174:177], v[198:201], v[38:41]
	v_mfma_f32_16x16x32_bf16 v[34:37], v[182:185], v[198:201], v[34:37]
	v_mfma_f32_16x16x32_bf16 v[22:25], v[174:177], v[220:223], v[22:25]
	v_mfma_f32_16x16x32_bf16 v[18:21], v[182:185], v[220:223], v[18:21]
	v_mfma_f32_16x16x32_bf16 v[6:9], v[174:177], v[228:231], v[6:9]
	v_mfma_f32_16x16x32_bf16 v[2:5], v[182:185], v[228:231], v[2:5]
	v_mfma_f32_16x16x32_bf16 v[54:57], v[178:181], v[194:197], v[54:57]
	v_mfma_f32_16x16x32_bf16 v[50:53], v[186:189], v[194:197], v[50:53]
	v_mfma_f32_16x16x32_bf16 v[38:41], v[178:181], v[202:205], v[38:41]
	v_mfma_f32_16x16x32_bf16 v[34:37], v[186:189], v[202:205], v[34:37]
	v_mfma_f32_16x16x32_bf16 v[22:25], v[178:181], v[224:227], v[22:25]
	v_mfma_f32_16x16x32_bf16 v[18:21], v[186:189], v[224:227], v[18:21]
	v_mfma_f32_16x16x32_bf16 v[6:9], v[178:181], v[232:235], v[6:9]
	v_mfma_f32_16x16x32_bf16 v[2:5], v[186:189], v[232:235], v[2:5]
	s_setprio 0
	s_barrier
	s_add_i32 s58, 0, 0x18000
	s_add_i32 s59, 0, 0x1c000
	v_add_u32_e32 v170, s58, v163
	v_add_u32_e32 v186, s59, v163
	ds_read_b128 v[152:155], v170
	ds_read_b128 v[156:159], v170 offset:1024
	ds_read_b128 v[166:169], v170 offset:2048
	ds_read_b128 v[170:173], v170 offset:3072
	ds_read_b128 v[174:177], v186
	ds_read_b128 v[178:181], v186 offset:1024
	ds_read_b128 v[182:185], v186 offset:2048
	ds_read_b128 v[186:189], v186 offset:3072
	s_add_u32 s18, s40, 0xb0000
	s_addc_u32 s19, s41, 0
	s_mov_b32 m0, s48
	v_lshl_add_u64 v[210:211], s[18:19], 0, v[134:135]
	ds_read_b128 v[190:193], v165 offset:32768
	ds_read_b128 v[194:197], v165 offset:33792
	ds_read_b128 v[198:201], v165 offset:34816
	ds_read_b128 v[202:205], v165 offset:35840
	ds_read_b128 v[220:223], v165 offset:36864
	ds_read_b128 v[224:227], v165 offset:37888
	ds_read_b128 v[228:231], v165 offset:38912
	ds_read_b128 v[232:235], v165 offset:39936
	global_load_lds_dwordx4 v[210:211], off
	v_lshl_add_u64 v[210:211], s[18:19], 0, v[132:133]
	s_mov_b32 m0, s49
	s_nop 0
	global_load_lds_dwordx4 v[210:211], off
	s_waitcnt vmcnt(8)
	s_waitcnt lgkmcnt(0)
	s_barrier
	s_setprio 1
	s_waitcnt lgkmcnt(0)
	v_mfma_f32_16x16x32_bf16 v[126:129], v[152:155], v[190:193], v[126:129]
	v_mfma_f32_16x16x32_bf16 v[122:125], v[166:169], v[190:193], v[122:125]
	v_mfma_f32_16x16x32_bf16 v[110:113], v[152:155], v[198:201], v[110:113]
	v_mfma_f32_16x16x32_bf16 v[106:109], v[166:169], v[198:201], v[106:109]
	v_mfma_f32_16x16x32_bf16 v[94:97], v[152:155], v[220:223], v[94:97]
	v_mfma_f32_16x16x32_bf16 v[90:93], v[166:169], v[220:223], v[90:93]
	v_mfma_f32_16x16x32_bf16 v[78:81], v[152:155], v[228:231], v[78:81]
	v_mfma_f32_16x16x32_bf16 v[74:77], v[166:169], v[228:231], v[74:77]
	v_mfma_f32_16x16x32_bf16 v[126:129], v[156:159], v[194:197], v[126:129]
	v_mfma_f32_16x16x32_bf16 v[122:125], v[170:173], v[194:197], v[122:125]
	v_mfma_f32_16x16x32_bf16 v[110:113], v[156:159], v[202:205], v[110:113]
	v_mfma_f32_16x16x32_bf16 v[106:109], v[170:173], v[202:205], v[106:109]
	v_mfma_f32_16x16x32_bf16 v[94:97], v[156:159], v[224:227], v[94:97]
	v_mfma_f32_16x16x32_bf16 v[90:93], v[170:173], v[224:227], v[90:93]
	v_mfma_f32_16x16x32_bf16 v[78:81], v[156:159], v[232:235], v[78:81]
	v_mfma_f32_16x16x32_bf16 v[74:77], v[170:173], v[232:235], v[74:77]
	s_setprio 0
	s_setprio 1
	v_mfma_f32_16x16x32_bf16 v[118:121], v[174:177], v[190:193], v[118:121]
	v_mfma_f32_16x16x32_bf16 v[114:117], v[182:185], v[190:193], v[114:117]
	v_mfma_f32_16x16x32_bf16 v[102:105], v[174:177], v[198:201], v[102:105]
	v_mfma_f32_16x16x32_bf16 v[98:101], v[182:185], v[198:201], v[98:101]
	v_mfma_f32_16x16x32_bf16 v[86:89], v[174:177], v[220:223], v[86:89]
	v_mfma_f32_16x16x32_bf16 v[82:85], v[182:185], v[220:223], v[82:85]
	v_mfma_f32_16x16x32_bf16 v[70:73], v[174:177], v[228:231], v[70:73]
	v_mfma_f32_16x16x32_bf16 v[66:69], v[182:185], v[228:231], v[66:69]
	v_mfma_f32_16x16x32_bf16 v[118:121], v[178:181], v[194:197], v[118:121]
	v_mfma_f32_16x16x32_bf16 v[114:117], v[186:189], v[194:197], v[114:117]
	v_mfma_f32_16x16x32_bf16 v[102:105], v[178:181], v[202:205], v[102:105]
	v_mfma_f32_16x16x32_bf16 v[98:101], v[186:189], v[202:205], v[98:101]
	v_mfma_f32_16x16x32_bf16 v[86:89], v[178:181], v[224:227], v[86:89]
	v_mfma_f32_16x16x32_bf16 v[82:85], v[186:189], v[224:227], v[82:85]
	v_mfma_f32_16x16x32_bf16 v[70:73], v[178:181], v[232:235], v[70:73]
	v_mfma_f32_16x16x32_bf16 v[66:69], v[186:189], v[232:235], v[66:69]
	s_setprio 0
	s_barrier
; #define PG8_STAGE(bufoff, gbase, voff) do { _Pragma("unroll") for (int _i = 0; _i < 2; ++_i) \
;         __builtin_amdgcn_global_load_lds((const unsigned*)((const char*)(gbase) + (voff)[_i]), (PG8_LAS unsigned*)(lds + (bufoff) + ldsw + _i * 8192), 16, 0, 0); } while (0)
; #define PG8_LDA(dst, b, h) do { _Pragma("unroll") for (int m = 0; m < 4; ++m) _Pragma("unroll") for (int k = 0; k < 2; ++k) dst[m][k] = *(const PG8_LAS bf16x8*)(lds + PG8_SA(b, h) + aoff + m * 2048 + k * 1024); } while (0)
; #define PG8_WAIT_V(n) asm volatile("s_waitcnt vmcnt(" #n ")" ::: "memory")
; template <class Epi, class Sched, bool ALIGN_EPI = false, bool SP2 = false>
; __device__ __forceinline__ void gemm_phase(PG8_LAS unsigned char* lds, const Gemm g, const Sched& S, const Epi& E) {
;     ...
;             PG8_LDA(At, 1, 1); PG8_STAGE(PG8_SB(1, 0), b3, voffB); PG8_STAGE(PG8_SB(1, 1), b3 + hstep, voffB); PG8_STAGE(PG8_SA(1, 0), a3, voffA);
;             PG8_WAIT_V(8); PG8_WAIT_L(0); PG8_BAR; PG8_MMA(1, 0, At, B0); PG8_MMA(1, 1, At, B1); PG8_BAR; PG8_SCHED;
;     __device__ __forceinline__ void operator()(const pg8::f32x4 (&acc)[2][2][4][2], const pg8::Unit& u, int wr, int wc, int fr, int fq) const {
;     ...
;                 const int row = row0 + ai * 128 + m * 16; const size_t off = (size_t)row * DM + col0; float sq = 0.f;
; #pragma unroll
;                 for (int bj = 0; bj < 2; ++bj) { const size_t o = off + bj * 128; f32x4 xa, xc;
;                     if (xin) { xa = *(const f32x4*)(xin + o); xc = *(const f32x4*)(xin + o + 4); }
;                     else { const u32x4 r4 = *(const u32x4*)(xin_b + o); xa[0] = blo(r4.x); xa[1] = bhi(r4.x); xa[2] = blo(r4.y); xa[3] = bhi(r4.y); xc[0] = blo(r4.z); xc[1] = bhi(r4.z); xc[2] = blo(r4.w); xc[3] = bhi(r4.w); }
;                     f32x4 va, vc;
;                     va[0] = xa[0] + acc[ai][bj][m][0][0]; va[1] = xa[1] + acc[ai][bj][m][0][1]; va[2] = xa[2] + acc[ai][bj][m][0][2]; va[3] = xa[3] + acc[ai][bj][m][0][3];
;                     vc[0] = xc[0] + acc[ai][bj][m][1][0]; vc[1] = xc[1] + acc[ai][bj][m][1][1]; vc[2] = xc[2] + acc[ai][bj][m][1][2]; vc[3] = xc[3] + acc[ai][bj][m][1][3];
;                     if (xout) { *(f32x4*)(xout + o) = va; *(f32x4*)(xout + o + 4) = vc; }
;                     if (xb) { u32x4 w; w.x = pk2(va[0], va[1]); w.y = pk2(va[2], va[3]); w.z = pk2(vc[0], vc[1]); w.w = pk2(vc[2], vc[3]); *(u32x4*)(xb + o) = w; }
	s_add_i32 s18, s58, s45
	v_lshl_add_u64 v[140:141], v[140:141], 0, s[20:21]
	s_mov_b32 m0, s18
	ds_read_b128 v[190:193], v165 offset:49152
	ds_read_b128 v[194:197], v165 offset:50176
	ds_read_b128 v[198:201], v165 offset:51200
	ds_read_b128 v[202:205], v165 offset:52224
	ds_read_b128 v[220:223], v165 offset:53248
	ds_read_b128 v[224:227], v165 offset:54272
	ds_read_b128 v[228:231], v165 offset:55296
	ds_read_b128 v[232:235], v165 offset:56320
	global_load_lds_dwordx4 v[140:141], off
	s_add_i32 m0, s18, 0x2000
	s_add_u32 s18, s26, 0xb0080
	v_lshl_add_u64 v[140:141], v[146:147], 0, s[20:21]
	s_addc_u32 s19, s27, 0
	s_add_i32 s26, s59, s45
	global_load_lds_dwordx4 v[140:141], off
	v_lshl_add_u64 v[140:141], s[18:19], 0, v[0:1]
	s_mov_b32 m0, s26
	s_nop 0
	global_load_lds_dwordx4 v[140:141], off
	v_lshl_add_u64 v[140:141], s[18:19], 0, v[130:131]
	s_add_i32 m0, s26, 0x2000
	s_nop 0
	global_load_lds_dwordx4 v[140:141], off
	v_lshl_add_u64 v[140:141], v[160:161], 0, s[20:21]
	s_mov_b32 m0, s51
	s_nop 0
	global_load_lds_dwordx4 v[140:141], off
	v_lshl_add_u64 v[140:141], v[206:207], 0, s[20:21]
	s_mov_b32 m0, s52
	s_nop 0
	global_load_lds_dwordx4 v[140:141], off
	s_waitcnt vmcnt(8)
	s_waitcnt lgkmcnt(0)
	s_barrier
	s_setprio 1
	s_waitcnt lgkmcnt(0)
	v_mfma_f32_16x16x32_bf16 v[62:65], v[152:155], v[190:193], v[62:65]
	v_mfma_f32_16x16x32_bf16 v[58:61], v[166:169], v[190:193], v[58:61]
	v_mfma_f32_16x16x32_bf16 v[46:49], v[152:155], v[198:201], v[46:49]
	v_mfma_f32_16x16x32_bf16 v[42:45], v[166:169], v[198:201], v[42:45]
	v_mfma_f32_16x16x32_bf16 v[30:33], v[152:155], v[220:223], v[30:33]
	v_mfma_f32_16x16x32_bf16 v[26:29], v[166:169], v[220:223], v[26:29]
	v_mfma_f32_16x16x32_bf16 v[14:17], v[152:155], v[228:231], v[14:17]
	v_mfma_f32_16x16x32_bf16 v[10:13], v[166:169], v[228:231], v[10:13]
	v_mfma_f32_16x16x32_bf16 v[62:65], v[156:159], v[194:197], v[62:65]
	v_mfma_f32_16x16x32_bf16 v[58:61], v[170:173], v[194:197], v[58:61]
	v_mfma_f32_16x16x32_bf16 v[46:49], v[156:159], v[202:205], v[46:49]
	v_mfma_f32_16x16x32_bf16 v[42:45], v[170:173], v[202:205], v[42:45]
	v_mfma_f32_16x16x32_bf16 v[30:33], v[156:159], v[224:227], v[30:33]
	v_mfma_f32_16x16x32_bf16 v[26:29], v[170:173], v[224:227], v[26:29]
	v_mfma_f32_16x16x32_bf16 v[14:17], v[156:159], v[232:235], v[14:17]
	v_mfma_f32_16x16x32_bf16 v[10:13], v[170:173], v[232:235], v[10:13]
	s_setprio 0
	s_setprio 1
	v_mfma_f32_16x16x32_bf16 v[54:57], v[174:177], v[190:193], v[54:57]
	v_mfma_f32_16x16x32_bf16 v[50:53], v[182:185], v[190:193], v[50:53]
	v_mfma_f32_16x16x32_bf16 v[38:41], v[174:177], v[198:201], v[38:41]
	v_mfma_f32_16x16x32_bf16 v[34:37], v[182:185], v[198:201], v[34:37]
	v_mfma_f32_16x16x32_bf16 v[22:25], v[174:177], v[220:223], v[22:25]
	v_mfma_f32_16x16x32_bf16 v[18:21], v[182:185], v[220:223], v[18:21]
	v_mfma_f32_16x16x32_bf16 v[6:9], v[174:177], v[228:231], v[6:9]
	v_mfma_f32_16x16x32_bf16 v[2:5], v[182:185], v[228:231], v[2:5]
	v_mfma_f32_16x16x32_bf16 v[54:57], v[178:181], v[194:197], v[54:57]
	v_mfma_f32_16x16x32_bf16 v[50:53], v[186:189], v[194:197], v[50:53]
	v_mfma_f32_16x16x32_bf16 v[38:41], v[178:181], v[202:205], v[38:41]
	v_mfma_f32_16x16x32_bf16 v[34:37], v[186:189], v[202:205], v[34:37]
	v_mfma_f32_16x16x32_bf16 v[22:25], v[178:181], v[224:227], v[22:25]
	v_mfma_f32_16x16x32_bf16 v[18:21], v[186:189], v[224:227], v[18:21]
	v_mfma_f32_16x16x32_bf16 v[6:9], v[178:181], v[232:235], v[6:9]
	v_mfma_f32_16x16x32_bf16 v[2:5], v[186:189], v[232:235], v[2:5]
	s_setprio 0
	s_barrier
	s_add_i32 s57, s57, 2
	s_add_u32 s55, s55, 0x100
	s_addc_u32 s56, s56, 0
	s_cmp_gt_u32 s57, 41
	s_mov_b64 s[18:19], s[24:25]
	s_cbranch_scc0 .LBB0_1604
	v_lshl_add_u32 v154, s43, 8, v162
	v_lshl_or_b32 v152, s42, 8, v164
	v_ashrrev_i32_e32 v155, 31, v154
	v_ashrrev_i32_e32 v153, 31, v152
	v_lshlrev_b64 v[140:141], 10, v[154:155]
	v_lshl_add_u64 v[158:159], v[140:141], 0, v[152:153]
	v_lshl_add_u64 v[160:161], v[158:159], 1, s[28:29]
	v_mov_b64_e32 v[234:235], v[160:161]
	s_mov_b32 s99, 0
	global_load_dwordx4 v[170:173], v[160:161], off
	global_load_dwordx4 v[174:177], v[160:161], off offset:256
	s_mov_b32 s98, 0x8000
	v_lshl_add_u64 v[232:233], v[160:161], 0, s[98:99]
	global_load_dwordx4 v[178:181], v[232:233], off
	global_load_dwordx4 v[182:185], v[232:233], off offset:256
	s_mov_b32 s98, 0x10000
	v_lshl_add_u64 v[232:233], v[160:161], 0, s[98:99]
	global_load_dwordx4 v[186:189], v[232:233], off
	global_load_dwordx4 v[190:193], v[232:233], off offset:256
	s_mov_b32 s98, 0x18000
	v_lshl_add_u64 v[232:233], v[160:161], 0, s[98:99]
	global_load_dwordx4 v[194:197], v[232:233], off
	global_load_dwordx4 v[198:201], v[232:233], off offset:256
	s_mov_b32 s98, 0x40000
	v_lshl_add_u64 v[232:233], v[160:161], 0, s[98:99]
	global_load_dwordx4 v[202:205], v[232:233], off
	global_load_dwordx4 v[220:223], v[232:233], off offset:256
	s_mov_b32 s98, 0x48000
	v_lshl_add_u64 v[232:233], v[160:161], 0, s[98:99]
	global_load_dwordx4 v[224:227], v[232:233], off
	global_load_dwordx4 v[228:231], v[232:233], off offset:256
	s_and_b64 vcc, exec, s[12:13]
	s_cbranch_vccz .LBB0_1607
	s_barrier
.LBB0_1607:
	s_andn2_b64 vcc, exec, s[14:15]
	v_lshl_add_u64 v[156:157], v[158:159], 2, s[8:9]
	s_waitcnt vmcnt(0)
	v_lshlrev_b32_e32 v140, 16, v170
	v_and_b32_e32 v141, 0xffff0000, v170
	v_pk_add_f32 v[126:127], v[126:127], v[140:141]
	v_lshlrev_b32_e32 v140, 16, v171
	v_and_b32_e32 v141, 0xffff0000, v171
	v_pk_add_f32 v[128:129], v[128:129], v[140:141]
	v_lshlrev_b32_e32 v140, 16, v172
	v_and_b32_e32 v141, 0xffff0000, v172
	v_pk_add_f32 v[122:123], v[122:123], v[140:141]
	v_lshlrev_b32_e32 v140, 16, v173
	v_and_b32_e32 v141, 0xffff0000, v173
	v_pk_add_f32 v[124:125], v[124:125], v[140:141]
	v_cndmask_b32_e64 v140, 0, 1, s[14:15]
	v_cmp_ne_u32_e64 s[40:41], 1, v140
	s_cbranch_vccnz .LBB0_1609
	global_store_dwordx4 v[156:157], v[126:129], off
	global_store_dwordx4 v[156:157], v[122:125], off offset:16

; __device__ __forceinline__ float blo(unsigned u) { return __uint_as_float(u << 16); }
; __device__ __forceinline__ float bhi(unsigned u) { return __uint_as_float(u & 0xffff0000u); }
; __device__ __forceinline__ unsigned pk2(float lo, float hi) { pk_f32x2_t v = {lo, hi}; pk_bf16x2_t b = __builtin_convertvector(v, pk_bf16x2_t); return __builtin_bit_cast(unsigned, b); }
;     __device__ __forceinline__ void operator()(const pg8::f32x4 (&acc)[2][2][4][2], const pg8::Unit& u, int wr, int wc, int fr, int fq) const {
;     ...
;                 for (int bj = 0; bj < 2; ++bj) { const size_t o = off + bj * 128; f32x4 xa, xc;
;                     if (xin) { xa = *(const f32x4*)(xin + o); xc = *(const f32x4*)(xin + o + 4); }
;                     else { const u32x4 r4 = *(const u32x4*)(xin_b + o); xa[0] = blo(r4.x); xa[1] = bhi(r4.x); xa[2] = blo(r4.y); xa[3] = bhi(r4.y); xc[0] = blo(r4.z); xc[1] = bhi(r4.z); xc[2] = blo(r4.w); xc[3] = bhi(r4.w); }
;                     f32x4 va, vc;
;                     va[0] = xa[0] + acc[ai][bj][m][0][0]; va[1] = xa[1] + acc[ai][bj][m][0][1]; va[2] = xa[2] + acc[ai][bj][m][0][2]; va[3] = xa[3] + acc[ai][bj][m][0][3];
;                     vc[0] = xc[0] + acc[ai][bj][m][1][0]; vc[1] = xc[1] + acc[ai][bj][m][1][1]; vc[2] = xc[2] + acc[ai][bj][m][1][2]; vc[3] = xc[3] + acc[ai][bj][m][1][3];
;                     if (xout) { *(f32x4*)(xout + o) = va; *(f32x4*)(xout + o + 4) = vc; }
;                     if (xb) { u32x4 w; w.x = pk2(va[0], va[1]); w.y = pk2(va[2], va[3]); w.z = pk2(vc[0], vc[1]); w.w = pk2(vc[2], vc[3]); *(u32x4*)(xb + o) = w; }
.LBB0_1611:
	v_lshlrev_b64 v[140:141], 1, v[158:159]
	v_or_b32_e32 v140, 0x100, v140
	v_lshl_add_u64 v[158:159], s[28:29], 0, v[140:141]
	s_nop 1
	s_and_b64 vcc, exec, s[40:41]
	v_lshlrev_b32_e32 v140, 16, v174
	v_and_b32_e32 v141, 0xffff0000, v174
	v_pk_add_f32 v[118:119], v[118:119], v[140:141]
	v_lshlrev_b32_e32 v140, 16, v175
	v_and_b32_e32 v141, 0xffff0000, v175
	v_pk_add_f32 v[120:121], v[120:121], v[140:141]
	v_lshlrev_b32_e32 v140, 16, v176
	v_and_b32_e32 v141, 0xffff0000, v176
	v_pk_add_f32 v[114:115], v[114:115], v[140:141]
	v_lshlrev_b32_e32 v140, 16, v177
	v_and_b32_e32 v141, 0xffff0000, v177
	v_pk_add_f32 v[116:117], v[116:117], v[140:141]
	s_cbranch_vccnz .LBB0_1613
	global_store_dwordx4 v[156:157], v[118:121], off offset:512
	global_store_dwordx4 v[156:157], v[114:117], off offset:528

; __device__ __forceinline__ float blo(unsigned u) { return __uint_as_float(u << 16); }
; __device__ __forceinline__ float bhi(unsigned u) { return __uint_as_float(u & 0xffff0000u); }
; __device__ __forceinline__ unsigned pk2(float lo, float hi) { pk_f32x2_t v = {lo, hi}; pk_bf16x2_t b = __builtin_convertvector(v, pk_bf16x2_t); return __builtin_bit_cast(unsigned, b); }
;     __device__ __forceinline__ void operator()(const pg8::f32x4 (&acc)[2][2][4][2], const pg8::Unit& u, int wr, int wc, int fr, int fq) const {
;     ...
;                 for (int bj = 0; bj < 2; ++bj) { const size_t o = off + bj * 128; f32x4 xa, xc;
;                     if (xin) { xa = *(const f32x4*)(xin + o); xc = *(const f32x4*)(xin + o + 4); }
;                     else { const u32x4 r4 = *(const u32x4*)(xin_b + o); xa[0] = blo(r4.x); xa[1] = bhi(r4.x); xa[2] = blo(r4.y); xa[3] = bhi(r4.y); xc[0] = blo(r4.z); xc[1] = bhi(r4.z); xc[2] = blo(r4.w); xc[3] = bhi(r4.w); }
;                     f32x4 va, vc;
;                     va[0] = xa[0] + acc[ai][bj][m][0][0]; va[1] = xa[1] + acc[ai][bj][m][0][1]; va[2] = xa[2] + acc[ai][bj][m][0][2]; va[3] = xa[3] + acc[ai][bj][m][0][3];
;                     vc[0] = xc[0] + acc[ai][bj][m][1][0]; vc[1] = xc[1] + acc[ai][bj][m][1][1]; vc[2] = xc[2] + acc[ai][bj][m][1][2]; vc[3] = xc[3] + acc[ai][bj][m][1][3];
;                     if (xout) { *(f32x4*)(xout + o) = va; *(f32x4*)(xout + o + 4) = vc; }
;                     if (xb) { u32x4 w; w.x = pk2(va[0], va[1]); w.y = pk2(va[2], va[3]); w.z = pk2(vc[0], vc[1]); w.w = pk2(vc[2], vc[3]); *(u32x4*)(xb + o) = w; }
.LBB0_1617:
	v_or_b32_e32 v114, 16, v154
	v_ashrrev_i32_e32 v115, 31, v114
	v_lshlrev_b64 v[116:117], 10, v[114:115]
	v_lshl_add_u64 v[118:119], v[116:117], 0, v[152:153]
	v_lshl_add_u64 v[120:121], v[118:119], 1, s[28:29]
	s_nop 1
	s_and_b64 vcc, exec, s[40:41]
	v_lshlrev_b32_e32 v116, 16, v178
	v_and_b32_e32 v117, 0xffff0000, v178
	v_pk_add_f32 v[110:111], v[110:111], v[116:117]
	v_lshlrev_b32_e32 v116, 16, v179
	v_and_b32_e32 v117, 0xffff0000, v179
	v_pk_add_f32 v[112:113], v[112:113], v[116:117]
	v_lshlrev_b32_e32 v116, 16, v180
	v_and_b32_e32 v117, 0xffff0000, v180
	v_pk_add_f32 v[106:107], v[106:107], v[116:117]
	v_lshlrev_b32_e32 v116, 16, v181
	v_and_b32_e32 v117, 0xffff0000, v181
	v_pk_add_f32 v[108:109], v[108:109], v[116:117]
	v_lshl_add_u64 v[116:117], v[118:119], 2, s[8:9]
	s_cbranch_vccnz .LBB0_1619
	global_store_dwordx4 v[116:117], v[110:113], off
	global_store_dwordx4 v[116:117], v[106:109], off offset:16

; __device__ __forceinline__ float blo(unsigned u) { return __uint_as_float(u << 16); }
; __device__ __forceinline__ float bhi(unsigned u) { return __uint_as_float(u & 0xffff0000u); }
; __device__ __forceinline__ unsigned pk2(float lo, float hi) { pk_f32x2_t v = {lo, hi}; pk_bf16x2_t b = __builtin_convertvector(v, pk_bf16x2_t); return __builtin_bit_cast(unsigned, b); }
;     __device__ __forceinline__ void operator()(const pg8::f32x4 (&acc)[2][2][4][2], const pg8::Unit& u, int wr, int wc, int fr, int fq) const {
;     ...
;                 for (int bj = 0; bj < 2; ++bj) { const size_t o = off + bj * 128; f32x4 xa, xc;
;                     if (xin) { xa = *(const f32x4*)(xin + o); xc = *(const f32x4*)(xin + o + 4); }
;                     else { const u32x4 r4 = *(const u32x4*)(xin_b + o); xa[0] = blo(r4.x); xa[1] = bhi(r4.x); xa[2] = blo(r4.y); xa[3] = bhi(r4.y); xc[0] = blo(r4.z); xc[1] = bhi(r4.z); xc[2] = blo(r4.w); xc[3] = bhi(r4.w); }
;                     f32x4 va, vc;
;                     va[0] = xa[0] + acc[ai][bj][m][0][0]; va[1] = xa[1] + acc[ai][bj][m][0][1]; va[2] = xa[2] + acc[ai][bj][m][0][2]; va[3] = xa[3] + acc[ai][bj][m][0][3];
;                     vc[0] = xc[0] + acc[ai][bj][m][1][0]; vc[1] = xc[1] + acc[ai][bj][m][1][1]; vc[2] = xc[2] + acc[ai][bj][m][1][2]; vc[3] = xc[3] + acc[ai][bj][m][1][3];
;                     if (xout) { *(f32x4*)(xout + o) = va; *(f32x4*)(xout + o + 4) = vc; }
;                     if (xb) { u32x4 w; w.x = pk2(va[0], va[1]); w.y = pk2(va[2], va[3]); w.z = pk2(vc[0], vc[1]); w.w = pk2(vc[2], vc[3]); *(u32x4*)(xb + o) = w; }
.LBB0_1621:
	v_lshlrev_b64 v[118:119], 1, v[118:119]
	v_or_b32_e32 v118, 0x100, v118
	v_lshl_add_u64 v[118:119], s[28:29], 0, v[118:119]
	s_nop 1
	s_and_b64 vcc, exec, s[40:41]
	v_lshlrev_b32_e32 v124, 16, v182
	v_and_b32_e32 v125, 0xffff0000, v182
	v_lshlrev_b32_e32 v120, 16, v183
	v_and_b32_e32 v121, 0xffff0000, v183
	v_pk_add_f32 v[104:105], v[104:105], v[120:121]
	v_lshlrev_b32_e32 v120, 16, v184
	v_and_b32_e32 v121, 0xffff0000, v184
	v_pk_add_f32 v[98:99], v[98:99], v[120:121]
	v_lshlrev_b32_e32 v120, 16, v185
	v_and_b32_e32 v121, 0xffff0000, v185
	v_pk_add_f32 v[102:103], v[102:103], v[124:125]
	v_pk_add_f32 v[100:101], v[100:101], v[120:121]
	s_cbranch_vccnz .LBB0_1623
	global_store_dwordx4 v[116:117], v[102:105], off offset:512
	global_store_dwordx4 v[116:117], v[98:101], off offset:528

; __device__ __forceinline__ float blo(unsigned u) { return __uint_as_float(u << 16); }
; __device__ __forceinline__ float bhi(unsigned u) { return __uint_as_float(u & 0xffff0000u); }
; __device__ __forceinline__ unsigned pk2(float lo, float hi) { pk_f32x2_t v = {lo, hi}; pk_bf16x2_t b = __builtin_convertvector(v, pk_bf16x2_t); return __builtin_bit_cast(unsigned, b); }
;     __device__ __forceinline__ void operator()(const pg8::f32x4 (&acc)[2][2][4][2], const pg8::Unit& u, int wr, int wc, int fr, int fq) const {
;     ...
;                 for (int bj = 0; bj < 2; ++bj) { const size_t o = off + bj * 128; f32x4 xa, xc;
;                     if (xin) { xa = *(const f32x4*)(xin + o); xc = *(const f32x4*)(xin + o + 4); }
;                     else { const u32x4 r4 = *(const u32x4*)(xin_b + o); xa[0] = blo(r4.x); xa[1] = bhi(r4.x); xa[2] = blo(r4.y); xa[3] = bhi(r4.y); xc[0] = blo(r4.z); xc[1] = bhi(r4.z); xc[2] = blo(r4.w); xc[3] = bhi(r4.w); }
;                     f32x4 va, vc;
;                     va[0] = xa[0] + acc[ai][bj][m][0][0]; va[1] = xa[1] + acc[ai][bj][m][0][1]; va[2] = xa[2] + acc[ai][bj][m][0][2]; va[3] = xa[3] + acc[ai][bj][m][0][3];
;                     vc[0] = xc[0] + acc[ai][bj][m][1][0]; vc[1] = xc[1] + acc[ai][bj][m][1][1]; vc[2] = xc[2] + acc[ai][bj][m][1][2]; vc[3] = xc[3] + acc[ai][bj][m][1][3];
;                     if (xout) { *(f32x4*)(xout + o) = va; *(f32x4*)(xout + o + 4) = vc; }
;                     if (xb) { u32x4 w; w.x = pk2(va[0], va[1]); w.y = pk2(va[2], va[3]); w.z = pk2(vc[0], vc[1]); w.w = pk2(vc[2], vc[3]); *(u32x4*)(xb + o) = w; }
.LBB0_1627:
	v_or_b32_e32 v98, 32, v154
	v_ashrrev_i32_e32 v99, 31, v98
	v_lshlrev_b64 v[100:101], 10, v[98:99]
	v_lshl_add_u64 v[102:103], v[100:101], 0, v[152:153]
	v_lshl_add_u64 v[104:105], v[102:103], 1, s[28:29]
	s_mov_b32 s98, 0x50000
	v_lshl_add_u64 v[232:233], v[234:235], 0, s[98:99]
	global_load_dwordx4 v[170:173], v[232:233], off
	global_load_dwordx4 v[174:177], v[232:233], off offset:256
	s_mov_b32 s98, 0x58000
	v_lshl_add_u64 v[232:233], v[234:235], 0, s[98:99]
	global_load_dwordx4 v[178:181], v[232:233], off
	global_load_dwordx4 v[182:185], v[232:233], off offset:256
	s_nop 1
	s_and_b64 vcc, exec, s[40:41]
	v_lshlrev_b32_e32 v100, 16, v186
	v_and_b32_e32 v101, 0xffff0000, v186
	v_pk_add_f32 v[94:95], v[94:95], v[100:101]
	v_lshlrev_b32_e32 v100, 16, v187
	v_and_b32_e32 v101, 0xffff0000, v187
	v_pk_add_f32 v[96:97], v[96:97], v[100:101]
	v_lshlrev_b32_e32 v100, 16, v188
	v_and_b32_e32 v101, 0xffff0000, v188
	v_pk_add_f32 v[90:91], v[90:91], v[100:101]
	v_lshlrev_b32_e32 v100, 16, v189
	v_and_b32_e32 v101, 0xffff0000, v189
	v_pk_add_f32 v[92:93], v[92:93], v[100:101]
	v_lshl_add_u64 v[100:101], v[102:103], 2, s[8:9]
	s_cbranch_vccnz .LBB0_1629
	global_store_dwordx4 v[100:101], v[94:97], off
	global_store_dwordx4 v[100:101], v[90:93], off offset:16

; __device__ __forceinline__ float blo(unsigned u) { return __uint_as_float(u << 16); }
; __device__ __forceinline__ float bhi(unsigned u) { return __uint_as_float(u & 0xffff0000u); }
; __device__ __forceinline__ unsigned pk2(float lo, float hi) { pk_f32x2_t v = {lo, hi}; pk_bf16x2_t b = __builtin_convertvector(v, pk_bf16x2_t); return __builtin_bit_cast(unsigned, b); }
;     __device__ __forceinline__ void operator()(const pg8::f32x4 (&acc)[2][2][4][2], const pg8::Unit& u, int wr, int wc, int fr, int fq) const {
;     ...
;                 for (int bj = 0; bj < 2; ++bj) { const size_t o = off + bj * 128; f32x4 xa, xc;
;                     if (xin) { xa = *(const f32x4*)(xin + o); xc = *(const f32x4*)(xin + o + 4); }
;                     else { const u32x4 r4 = *(const u32x4*)(xin_b + o); xa[0] = blo(r4.x); xa[1] = bhi(r4.x); xa[2] = blo(r4.y); xa[3] = bhi(r4.y); xc[0] = blo(r4.z); xc[1] = bhi(r4.z); xc[2] = blo(r4.w); xc[3] = bhi(r4.w); }
;                     f32x4 va, vc;
;                     va[0] = xa[0] + acc[ai][bj][m][0][0]; va[1] = xa[1] + acc[ai][bj][m][0][1]; va[2] = xa[2] + acc[ai][bj][m][0][2]; va[3] = xa[3] + acc[ai][bj][m][0][3];
;                     vc[0] = xc[0] + acc[ai][bj][m][1][0]; vc[1] = xc[1] + acc[ai][bj][m][1][1]; vc[2] = xc[2] + acc[ai][bj][m][1][2]; vc[3] = xc[3] + acc[ai][bj][m][1][3];
;                     if (xout) { *(f32x4*)(xout + o) = va; *(f32x4*)(xout + o + 4) = vc; }
;                     if (xb) { u32x4 w; w.x = pk2(va[0], va[1]); w.y = pk2(va[2], va[3]); w.z = pk2(vc[0], vc[1]); w.w = pk2(vc[2], vc[3]); *(u32x4*)(xb + o) = w; }
.LBB0_1631:
	v_lshlrev_b64 v[102:103], 1, v[102:103]
	v_or_b32_e32 v102, 0x100, v102
	v_lshl_add_u64 v[102:103], s[28:29], 0, v[102:103]
	s_nop 1
	s_and_b64 vcc, exec, s[40:41]
	v_lshlrev_b32_e32 v108, 16, v190
	v_and_b32_e32 v109, 0xffff0000, v190
	v_lshlrev_b32_e32 v104, 16, v191
	v_and_b32_e32 v105, 0xffff0000, v191
	v_pk_add_f32 v[88:89], v[88:89], v[104:105]
	v_lshlrev_b32_e32 v104, 16, v192
	v_and_b32_e32 v105, 0xffff0000, v192
	v_pk_add_f32 v[82:83], v[82:83], v[104:105]
	v_lshlrev_b32_e32 v104, 16, v193
	v_and_b32_e32 v105, 0xffff0000, v193
	v_pk_add_f32 v[86:87], v[86:87], v[108:109]
	v_pk_add_f32 v[84:85], v[84:85], v[104:105]
	s_cbranch_vccnz .LBB0_1633
	global_store_dwordx4 v[100:101], v[86:89], off offset:512
	global_store_dwordx4 v[100:101], v[82:85], off offset:528

; __device__ __forceinline__ float blo(unsigned u) { return __uint_as_float(u << 16); }
; __device__ __forceinline__ float bhi(unsigned u) { return __uint_as_float(u & 0xffff0000u); }
; __device__ __forceinline__ unsigned pk2(float lo, float hi) { pk_f32x2_t v = {lo, hi}; pk_bf16x2_t b = __builtin_convertvector(v, pk_bf16x2_t); return __builtin_bit_cast(unsigned, b); }
;     __device__ __forceinline__ void operator()(const pg8::f32x4 (&acc)[2][2][4][2], const pg8::Unit& u, int wr, int wc, int fr, int fq) const {
;     ...
;                 for (int bj = 0; bj < 2; ++bj) { const size_t o = off + bj * 128; f32x4 xa, xc;
;                     if (xin) { xa = *(const f32x4*)(xin + o); xc = *(const f32x4*)(xin + o + 4); }
;                     else { const u32x4 r4 = *(const u32x4*)(xin_b + o); xa[0] = blo(r4.x); xa[1] = bhi(r4.x); xa[2] = blo(r4.y); xa[3] = bhi(r4.y); xc[0] = blo(r4.z); xc[1] = bhi(r4.z); xc[2] = blo(r4.w); xc[3] = bhi(r4.w); }
;                     f32x4 va, vc;
;                     va[0] = xa[0] + acc[ai][bj][m][0][0]; va[1] = xa[1] + acc[ai][bj][m][0][1]; va[2] = xa[2] + acc[ai][bj][m][0][2]; va[3] = xa[3] + acc[ai][bj][m][0][3];
;                     vc[0] = xc[0] + acc[ai][bj][m][1][0]; vc[1] = xc[1] + acc[ai][bj][m][1][1]; vc[2] = xc[2] + acc[ai][bj][m][1][2]; vc[3] = xc[3] + acc[ai][bj][m][1][3];
;                     if (xout) { *(f32x4*)(xout + o) = va; *(f32x4*)(xout + o + 4) = vc; }
;                     if (xb) { u32x4 w; w.x = pk2(va[0], va[1]); w.y = pk2(va[2], va[3]); w.z = pk2(vc[0], vc[1]); w.w = pk2(vc[2], vc[3]); *(u32x4*)(xb + o) = w; }
.LBB0_1637:
	v_or_b32_e32 v82, 48, v154
	v_ashrrev_i32_e32 v83, 31, v82
	v_lshlrev_b64 v[84:85], 10, v[82:83]
	v_lshl_add_u64 v[86:87], v[84:85], 0, v[152:153]
	v_lshl_add_u64 v[88:89], v[86:87], 1, s[28:29]
	s_nop 1
	s_and_b64 vcc, exec, s[40:41]
	v_lshlrev_b32_e32 v84, 16, v194
	v_and_b32_e32 v85, 0xffff0000, v194
	v_pk_add_f32 v[78:79], v[78:79], v[84:85]
	v_lshlrev_b32_e32 v84, 16, v195
	v_and_b32_e32 v85, 0xffff0000, v195
	v_pk_add_f32 v[80:81], v[80:81], v[84:85]
	v_lshlrev_b32_e32 v84, 16, v196
	v_and_b32_e32 v85, 0xffff0000, v196
	v_pk_add_f32 v[74:75], v[74:75], v[84:85]
	v_lshlrev_b32_e32 v84, 16, v197
	v_and_b32_e32 v85, 0xffff0000, v197
	v_pk_add_f32 v[76:77], v[76:77], v[84:85]
	v_lshl_add_u64 v[84:85], v[86:87], 2, s[8:9]
	s_cbranch_vccnz .LBB0_1639
	global_store_dwordx4 v[84:85], v[78:81], off
	global_store_dwordx4 v[84:85], v[74:77], off offset:16

; __device__ __forceinline__ float blo(unsigned u) { return __uint_as_float(u << 16); }
; __device__ __forceinline__ float bhi(unsigned u) { return __uint_as_float(u & 0xffff0000u); }
; __device__ __forceinline__ unsigned pk2(float lo, float hi) { pk_f32x2_t v = {lo, hi}; pk_bf16x2_t b = __builtin_convertvector(v, pk_bf16x2_t); return __builtin_bit_cast(unsigned, b); }
;     __device__ __forceinline__ void operator()(const pg8::f32x4 (&acc)[2][2][4][2], const pg8::Unit& u, int wr, int wc, int fr, int fq) const {
;     ...
;                 for (int bj = 0; bj < 2; ++bj) { const size_t o = off + bj * 128; f32x4 xa, xc;
;                     if (xin) { xa = *(const f32x4*)(xin + o); xc = *(const f32x4*)(xin + o + 4); }
;                     else { const u32x4 r4 = *(const u32x4*)(xin_b + o); xa[0] = blo(r4.x); xa[1] = bhi(r4.x); xa[2] = blo(r4.y); xa[3] = bhi(r4.y); xc[0] = blo(r4.z); xc[1] = bhi(r4.z); xc[2] = blo(r4.w); xc[3] = bhi(r4.w); }
;                     f32x4 va, vc;
;                     va[0] = xa[0] + acc[ai][bj][m][0][0]; va[1] = xa[1] + acc[ai][bj][m][0][1]; va[2] = xa[2] + acc[ai][bj][m][0][2]; va[3] = xa[3] + acc[ai][bj][m][0][3];
;                     vc[0] = xc[0] + acc[ai][bj][m][1][0]; vc[1] = xc[1] + acc[ai][bj][m][1][1]; vc[2] = xc[2] + acc[ai][bj][m][1][2]; vc[3] = xc[3] + acc[ai][bj][m][1][3];
;                     if (xout) { *(f32x4*)(xout + o) = va; *(f32x4*)(xout + o + 4) = vc; }
;                     if (xb) { u32x4 w; w.x = pk2(va[0], va[1]); w.y = pk2(va[2], va[3]); w.z = pk2(vc[0], vc[1]); w.w = pk2(vc[2], vc[3]); *(u32x4*)(xb + o) = w; }
.LBB0_1641:
	v_lshlrev_b64 v[86:87], 1, v[86:87]
	v_or_b32_e32 v86, 0x100, v86
	v_lshl_add_u64 v[86:87], s[28:29], 0, v[86:87]
	s_nop 1
	s_and_b64 vcc, exec, s[40:41]
	v_lshlrev_b32_e32 v92, 16, v198
	v_and_b32_e32 v93, 0xffff0000, v198
	v_lshlrev_b32_e32 v88, 16, v199
	v_and_b32_e32 v89, 0xffff0000, v199
	v_pk_add_f32 v[72:73], v[72:73], v[88:89]
	v_lshlrev_b32_e32 v88, 16, v200
	v_and_b32_e32 v89, 0xffff0000, v200
	v_pk_add_f32 v[66:67], v[66:67], v[88:89]
	v_lshlrev_b32_e32 v88, 16, v201
	v_and_b32_e32 v89, 0xffff0000, v201
	v_pk_add_f32 v[70:71], v[70:71], v[92:93]
	v_pk_add_f32 v[68:69], v[68:69], v[88:89]
	s_cbranch_vccnz .LBB0_1643
	global_store_dwordx4 v[84:85], v[70:73], off offset:512
	global_store_dwordx4 v[84:85], v[66:69], off offset:528

; __device__ __forceinline__ float blo(unsigned u) { return __uint_as_float(u << 16); }
; __device__ __forceinline__ float bhi(unsigned u) { return __uint_as_float(u & 0xffff0000u); }
; __device__ __forceinline__ unsigned pk2(float lo, float hi) { pk_f32x2_t v = {lo, hi}; pk_bf16x2_t b = __builtin_convertvector(v, pk_bf16x2_t); return __builtin_bit_cast(unsigned, b); }
;     __device__ __forceinline__ void operator()(const pg8::f32x4 (&acc)[2][2][4][2], const pg8::Unit& u, int wr, int wc, int fr, int fq) const {
;     ...
;                 for (int bj = 0; bj < 2; ++bj) { const size_t o = off + bj * 128; f32x4 xa, xc;
;                     if (xin) { xa = *(const f32x4*)(xin + o); xc = *(const f32x4*)(xin + o + 4); }
;                     else { const u32x4 r4 = *(const u32x4*)(xin_b + o); xa[0] = blo(r4.x); xa[1] = bhi(r4.x); xa[2] = blo(r4.y); xa[3] = bhi(r4.y); xc[0] = blo(r4.z); xc[1] = bhi(r4.z); xc[2] = blo(r4.w); xc[3] = bhi(r4.w); }
;                     f32x4 va, vc;
;                     va[0] = xa[0] + acc[ai][bj][m][0][0]; va[1] = xa[1] + acc[ai][bj][m][0][1]; va[2] = xa[2] + acc[ai][bj][m][0][2]; va[3] = xa[3] + acc[ai][bj][m][0][3];
;                     vc[0] = xc[0] + acc[ai][bj][m][1][0]; vc[1] = xc[1] + acc[ai][bj][m][1][1]; vc[2] = xc[2] + acc[ai][bj][m][1][2]; vc[3] = xc[3] + acc[ai][bj][m][1][3];
;                     if (xout) { *(f32x4*)(xout + o) = va; *(f32x4*)(xout + o + 4) = vc; }
;                     if (xb) { u32x4 w; w.x = pk2(va[0], va[1]); w.y = pk2(va[2], va[3]); w.z = pk2(vc[0], vc[1]); w.w = pk2(vc[2], vc[3]); *(u32x4*)(xb + o) = w; }
.LBB0_1647:
	v_add_u32_e32 v66, 0x80, v154
	v_ashrrev_i32_e32 v67, 31, v66
	v_lshlrev_b64 v[68:69], 10, v[66:67]
	v_lshl_add_u64 v[70:71], v[68:69], 0, v[152:153]
	v_lshl_add_u64 v[72:73], v[70:71], 1, s[28:29]
	s_nop 1
	s_and_b64 vcc, exec, s[40:41]
	v_lshlrev_b32_e32 v68, 16, v202
	v_and_b32_e32 v69, 0xffff0000, v202
	v_pk_add_f32 v[62:63], v[62:63], v[68:69]
	v_lshlrev_b32_e32 v68, 16, v203
	v_and_b32_e32 v69, 0xffff0000, v203
	v_pk_add_f32 v[64:65], v[64:65], v[68:69]
	v_lshlrev_b32_e32 v68, 16, v204
	v_and_b32_e32 v69, 0xffff0000, v204
	v_pk_add_f32 v[58:59], v[58:59], v[68:69]
	v_lshlrev_b32_e32 v68, 16, v205
	v_and_b32_e32 v69, 0xffff0000, v205
	v_pk_add_f32 v[60:61], v[60:61], v[68:69]
	v_lshl_add_u64 v[68:69], v[70:71], 2, s[8:9]
	s_cbranch_vccnz .LBB0_1649
	global_store_dwordx4 v[68:69], v[62:65], off
	global_store_dwordx4 v[68:69], v[58:61], off offset:16

; __device__ __forceinline__ float blo(unsigned u) { return __uint_as_float(u << 16); }
; __device__ __forceinline__ float bhi(unsigned u) { return __uint_as_float(u & 0xffff0000u); }
; __device__ __forceinline__ unsigned pk2(float lo, float hi) { pk_f32x2_t v = {lo, hi}; pk_bf16x2_t b = __builtin_convertvector(v, pk_bf16x2_t); return __builtin_bit_cast(unsigned, b); }
;     __device__ __forceinline__ void operator()(const pg8::f32x4 (&acc)[2][2][4][2], const pg8::Unit& u, int wr, int wc, int fr, int fq) const {
;     ...
;                 for (int bj = 0; bj < 2; ++bj) { const size_t o = off + bj * 128; f32x4 xa, xc;
;                     if (xin) { xa = *(const f32x4*)(xin + o); xc = *(const f32x4*)(xin + o + 4); }
;                     else { const u32x4 r4 = *(const u32x4*)(xin_b + o); xa[0] = blo(r4.x); xa[1] = bhi(r4.x); xa[2] = blo(r4.y); xa[3] = bhi(r4.y); xc[0] = blo(r4.z); xc[1] = bhi(r4.z); xc[2] = blo(r4.w); xc[3] = bhi(r4.w); }
;                     f32x4 va, vc;
;                     va[0] = xa[0] + acc[ai][bj][m][0][0]; va[1] = xa[1] + acc[ai][bj][m][0][1]; va[2] = xa[2] + acc[ai][bj][m][0][2]; va[3] = xa[3] + acc[ai][bj][m][0][3];
;                     vc[0] = xc[0] + acc[ai][bj][m][1][0]; vc[1] = xc[1] + acc[ai][bj][m][1][1]; vc[2] = xc[2] + acc[ai][bj][m][1][2]; vc[3] = xc[3] + acc[ai][bj][m][1][3];
;                     if (xout) { *(f32x4*)(xout + o) = va; *(f32x4*)(xout + o + 4) = vc; }
;                     if (xb) { u32x4 w; w.x = pk2(va[0], va[1]); w.y = pk2(va[2], va[3]); w.z = pk2(vc[0], vc[1]); w.w = pk2(vc[2], vc[3]); *(u32x4*)(xb + o) = w; }
.LBB0_1651:
	v_lshlrev_b64 v[70:71], 1, v[70:71]
	v_or_b32_e32 v70, 0x100, v70
	v_lshl_add_u64 v[70:71], s[28:29], 0, v[70:71]
	s_nop 1
	s_and_b64 vcc, exec, s[40:41]
	v_lshlrev_b32_e32 v76, 16, v220
	v_and_b32_e32 v77, 0xffff0000, v220
	v_lshlrev_b32_e32 v72, 16, v221
	v_and_b32_e32 v73, 0xffff0000, v221
	v_pk_add_f32 v[56:57], v[56:57], v[72:73]
	v_lshlrev_b32_e32 v72, 16, v222
	v_and_b32_e32 v73, 0xffff0000, v222
	v_pk_add_f32 v[50:51], v[50:51], v[72:73]
	v_lshlrev_b32_e32 v72, 16, v223
	v_and_b32_e32 v73, 0xffff0000, v223
	v_pk_add_f32 v[54:55], v[54:55], v[76:77]
	v_pk_add_f32 v[52:53], v[52:53], v[72:73]
	s_cbranch_vccnz .LBB0_1653
	global_store_dwordx4 v[68:69], v[54:57], off offset:512
	global_store_dwordx4 v[68:69], v[50:53], off offset:528

; __device__ __forceinline__ float blo(unsigned u) { return __uint_as_float(u << 16); }
; __device__ __forceinline__ float bhi(unsigned u) { return __uint_as_float(u & 0xffff0000u); }
; __device__ __forceinline__ unsigned pk2(float lo, float hi) { pk_f32x2_t v = {lo, hi}; pk_bf16x2_t b = __builtin_convertvector(v, pk_bf16x2_t); return __builtin_bit_cast(unsigned, b); }
;     __device__ __forceinline__ void operator()(const pg8::f32x4 (&acc)[2][2][4][2], const pg8::Unit& u, int wr, int wc, int fr, int fq) const {
;     ...
;                 for (int bj = 0; bj < 2; ++bj) { const size_t o = off + bj * 128; f32x4 xa, xc;
;                     if (xin) { xa = *(const f32x4*)(xin + o); xc = *(const f32x4*)(xin + o + 4); }
;                     else { const u32x4 r4 = *(const u32x4*)(xin_b + o); xa[0] = blo(r4.x); xa[1] = bhi(r4.x); xa[2] = blo(r4.y); xa[3] = bhi(r4.y); xc[0] = blo(r4.z); xc[1] = bhi(r4.z); xc[2] = blo(r4.w); xc[3] = bhi(r4.w); }
;                     f32x4 va, vc;
;                     va[0] = xa[0] + acc[ai][bj][m][0][0]; va[1] = xa[1] + acc[ai][bj][m][0][1]; va[2] = xa[2] + acc[ai][bj][m][0][2]; va[3] = xa[3] + acc[ai][bj][m][0][3];
;                     vc[0] = xc[0] + acc[ai][bj][m][1][0]; vc[1] = xc[1] + acc[ai][bj][m][1][1]; vc[2] = xc[2] + acc[ai][bj][m][1][2]; vc[3] = xc[3] + acc[ai][bj][m][1][3];
;                     if (xout) { *(f32x4*)(xout + o) = va; *(f32x4*)(xout + o + 4) = vc; }
;                     if (xb) { u32x4 w; w.x = pk2(va[0], va[1]); w.y = pk2(va[2], va[3]); w.z = pk2(vc[0], vc[1]); w.w = pk2(vc[2], vc[3]); *(u32x4*)(xb + o) = w; }
.LBB0_1657:
	v_add_u32_e32 v50, 0x90, v154
	v_ashrrev_i32_e32 v51, 31, v50
	v_lshlrev_b64 v[52:53], 10, v[50:51]
	v_lshl_add_u64 v[54:55], v[52:53], 0, v[152:153]
	v_lshl_add_u64 v[56:57], v[54:55], 1, s[28:29]
	s_nop 1
	s_and_b64 vcc, exec, s[40:41]
	v_lshlrev_b32_e32 v52, 16, v224
	v_and_b32_e32 v53, 0xffff0000, v224
	v_pk_add_f32 v[46:47], v[46:47], v[52:53]
	v_lshlrev_b32_e32 v52, 16, v225
	v_and_b32_e32 v53, 0xffff0000, v225
	v_pk_add_f32 v[48:49], v[48:49], v[52:53]
	v_lshlrev_b32_e32 v52, 16, v226
	v_and_b32_e32 v53, 0xffff0000, v226
	v_pk_add_f32 v[42:43], v[42:43], v[52:53]
	v_lshlrev_b32_e32 v52, 16, v227
	v_and_b32_e32 v53, 0xffff0000, v227
	v_pk_add_f32 v[44:45], v[44:45], v[52:53]
	v_lshl_add_u64 v[52:53], v[54:55], 2, s[8:9]
	s_cbranch_vccnz .LBB0_1659
	global_store_dwordx4 v[52:53], v[46:49], off
	global_store_dwordx4 v[52:53], v[42:45], off offset:16

; __device__ __forceinline__ float blo(unsigned u) { return __uint_as_float(u << 16); }
; __device__ __forceinline__ float bhi(unsigned u) { return __uint_as_float(u & 0xffff0000u); }
; __device__ __forceinline__ unsigned pk2(float lo, float hi) { pk_f32x2_t v = {lo, hi}; pk_bf16x2_t b = __builtin_convertvector(v, pk_bf16x2_t); return __builtin_bit_cast(unsigned, b); }
;     __device__ __forceinline__ void operator()(const pg8::f32x4 (&acc)[2][2][4][2], const pg8::Unit& u, int wr, int wc, int fr, int fq) const {
;     ...
;                 for (int bj = 0; bj < 2; ++bj) { const size_t o = off + bj * 128; f32x4 xa, xc;
;                     if (xin) { xa = *(const f32x4*)(xin + o); xc = *(const f32x4*)(xin + o + 4); }
;                     else { const u32x4 r4 = *(const u32x4*)(xin_b + o); xa[0] = blo(r4.x); xa[1] = bhi(r4.x); xa[2] = blo(r4.y); xa[3] = bhi(r4.y); xc[0] = blo(r4.z); xc[1] = bhi(r4.z); xc[2] = blo(r4.w); xc[3] = bhi(r4.w); }
;                     f32x4 va, vc;
;                     va[0] = xa[0] + acc[ai][bj][m][0][0]; va[1] = xa[1] + acc[ai][bj][m][0][1]; va[2] = xa[2] + acc[ai][bj][m][0][2]; va[3] = xa[3] + acc[ai][bj][m][0][3];
;                     vc[0] = xc[0] + acc[ai][bj][m][1][0]; vc[1] = xc[1] + acc[ai][bj][m][1][1]; vc[2] = xc[2] + acc[ai][bj][m][1][2]; vc[3] = xc[3] + acc[ai][bj][m][1][3];
;                     if (xout) { *(f32x4*)(xout + o) = va; *(f32x4*)(xout + o + 4) = vc; }
;                     if (xb) { u32x4 w; w.x = pk2(va[0], va[1]); w.y = pk2(va[2], va[3]); w.z = pk2(vc[0], vc[1]); w.w = pk2(vc[2], vc[3]); *(u32x4*)(xb + o) = w; }
.LBB0_1661:
	v_lshlrev_b64 v[54:55], 1, v[54:55]
	v_or_b32_e32 v54, 0x100, v54
	v_lshl_add_u64 v[54:55], s[28:29], 0, v[54:55]
	s_nop 1
	s_and_b64 vcc, exec, s[40:41]
	v_lshlrev_b32_e32 v60, 16, v228
	v_and_b32_e32 v61, 0xffff0000, v228
	v_lshlrev_b32_e32 v56, 16, v229
	v_and_b32_e32 v57, 0xffff0000, v229
	v_pk_add_f32 v[40:41], v[40:41], v[56:57]
	v_lshlrev_b32_e32 v56, 16, v230
	v_and_b32_e32 v57, 0xffff0000, v230
	v_pk_add_f32 v[34:35], v[34:35], v[56:57]
	v_lshlrev_b32_e32 v56, 16, v231
	v_and_b32_e32 v57, 0xffff0000, v231
	v_pk_add_f32 v[38:39], v[38:39], v[60:61]
	v_pk_add_f32 v[36:37], v[36:37], v[56:57]
	s_cbranch_vccnz .LBB0_1663
	global_store_dwordx4 v[52:53], v[38:41], off offset:512
	global_store_dwordx4 v[52:53], v[34:37], off offset:528

; __device__ __forceinline__ float blo(unsigned u) { return __uint_as_float(u << 16); }
; __device__ __forceinline__ float bhi(unsigned u) { return __uint_as_float(u & 0xffff0000u); }
; __device__ __forceinline__ unsigned pk2(float lo, float hi) { pk_f32x2_t v = {lo, hi}; pk_bf16x2_t b = __builtin_convertvector(v, pk_bf16x2_t); return __builtin_bit_cast(unsigned, b); }
;     __device__ __forceinline__ void operator()(const pg8::f32x4 (&acc)[2][2][4][2], const pg8::Unit& u, int wr, int wc, int fr, int fq) const {
;     ...
;                 for (int bj = 0; bj < 2; ++bj) { const size_t o = off + bj * 128; f32x4 xa, xc;
;                     if (xin) { xa = *(const f32x4*)(xin + o); xc = *(const f32x4*)(xin + o + 4); }
;                     else { const u32x4 r4 = *(const u32x4*)(xin_b + o); xa[0] = blo(r4.x); xa[1] = bhi(r4.x); xa[2] = blo(r4.y); xa[3] = bhi(r4.y); xc[0] = blo(r4.z); xc[1] = bhi(r4.z); xc[2] = blo(r4.w); xc[3] = bhi(r4.w); }
;                     f32x4 va, vc;
;                     va[0] = xa[0] + acc[ai][bj][m][0][0]; va[1] = xa[1] + acc[ai][bj][m][0][1]; va[2] = xa[2] + acc[ai][bj][m][0][2]; va[3] = xa[3] + acc[ai][bj][m][0][3];
;                     vc[0] = xc[0] + acc[ai][bj][m][1][0]; vc[1] = xc[1] + acc[ai][bj][m][1][1]; vc[2] = xc[2] + acc[ai][bj][m][1][2]; vc[3] = xc[3] + acc[ai][bj][m][1][3];
;                     if (xout) { *(f32x4*)(xout + o) = va; *(f32x4*)(xout + o + 4) = vc; }
;                     if (xb) { u32x4 w; w.x = pk2(va[0], va[1]); w.y = pk2(va[2], va[3]); w.z = pk2(vc[0], vc[1]); w.w = pk2(vc[2], vc[3]); *(u32x4*)(xb + o) = w; }
.LBB0_1667:
	v_add_u32_e32 v34, 0xa0, v154
	v_ashrrev_i32_e32 v35, 31, v34
	v_lshlrev_b64 v[36:37], 10, v[34:35]
	v_lshl_add_u64 v[38:39], v[36:37], 0, v[152:153]
	v_lshl_add_u64 v[40:41], v[38:39], 1, s[28:29]
	s_nop 1
	s_and_b64 vcc, exec, s[40:41]
	s_waitcnt vmcnt(0)
	v_lshlrev_b32_e32 v36, 16, v170
	v_and_b32_e32 v37, 0xffff0000, v170
	v_pk_add_f32 v[30:31], v[30:31], v[36:37]
	v_lshlrev_b32_e32 v36, 16, v171
	v_and_b32_e32 v37, 0xffff0000, v171
	v_pk_add_f32 v[32:33], v[32:33], v[36:37]
	v_lshlrev_b32_e32 v36, 16, v172
	v_and_b32_e32 v37, 0xffff0000, v172
	v_pk_add_f32 v[26:27], v[26:27], v[36:37]
	v_lshlrev_b32_e32 v36, 16, v173
	v_and_b32_e32 v37, 0xffff0000, v173
	v_pk_add_f32 v[28:29], v[28:29], v[36:37]
	v_lshl_add_u64 v[36:37], v[38:39], 2, s[8:9]
	s_cbranch_vccnz .LBB0_1669
	global_store_dwordx4 v[36:37], v[30:33], off
	global_store_dwordx4 v[36:37], v[26:29], off offset:16

; __device__ __forceinline__ float blo(unsigned u) { return __uint_as_float(u << 16); }
; __device__ __forceinline__ float bhi(unsigned u) { return __uint_as_float(u & 0xffff0000u); }
; __device__ __forceinline__ unsigned pk2(float lo, float hi) { pk_f32x2_t v = {lo, hi}; pk_bf16x2_t b = __builtin_convertvector(v, pk_bf16x2_t); return __builtin_bit_cast(unsigned, b); }
;     __device__ __forceinline__ void operator()(const pg8::f32x4 (&acc)[2][2][4][2], const pg8::Unit& u, int wr, int wc, int fr, int fq) const {
;     ...
;                 for (int bj = 0; bj < 2; ++bj) { const size_t o = off + bj * 128; f32x4 xa, xc;
;                     if (xin) { xa = *(const f32x4*)(xin + o); xc = *(const f32x4*)(xin + o + 4); }
;                     else { const u32x4 r4 = *(const u32x4*)(xin_b + o); xa[0] = blo(r4.x); xa[1] = bhi(r4.x); xa[2] = blo(r4.y); xa[3] = bhi(r4.y); xc[0] = blo(r4.z); xc[1] = bhi(r4.z); xc[2] = blo(r4.w); xc[3] = bhi(r4.w); }
;                     f32x4 va, vc;
;                     va[0] = xa[0] + acc[ai][bj][m][0][0]; va[1] = xa[1] + acc[ai][bj][m][0][1]; va[2] = xa[2] + acc[ai][bj][m][0][2]; va[3] = xa[3] + acc[ai][bj][m][0][3];
;                     vc[0] = xc[0] + acc[ai][bj][m][1][0]; vc[1] = xc[1] + acc[ai][bj][m][1][1]; vc[2] = xc[2] + acc[ai][bj][m][1][2]; vc[3] = xc[3] + acc[ai][bj][m][1][3];
;                     if (xout) { *(f32x4*)(xout + o) = va; *(f32x4*)(xout + o + 4) = vc; }
;                     if (xb) { u32x4 w; w.x = pk2(va[0], va[1]); w.y = pk2(va[2], va[3]); w.z = pk2(vc[0], vc[1]); w.w = pk2(vc[2], vc[3]); *(u32x4*)(xb + o) = w; }
.LBB0_1671:
	v_lshlrev_b64 v[38:39], 1, v[38:39]
	v_or_b32_e32 v38, 0x100, v38
	v_lshl_add_u64 v[38:39], s[28:29], 0, v[38:39]
	s_nop 1
	s_and_b64 vcc, exec, s[40:41]
	v_lshlrev_b32_e32 v44, 16, v174
	v_and_b32_e32 v45, 0xffff0000, v174
	v_lshlrev_b32_e32 v40, 16, v175
	v_and_b32_e32 v41, 0xffff0000, v175
	v_pk_add_f32 v[24:25], v[24:25], v[40:41]
	v_lshlrev_b32_e32 v40, 16, v176
	v_and_b32_e32 v41, 0xffff0000, v176
	v_pk_add_f32 v[18:19], v[18:19], v[40:41]
	v_lshlrev_b32_e32 v40, 16, v177
	v_and_b32_e32 v41, 0xffff0000, v177
	v_pk_add_f32 v[22:23], v[22:23], v[44:45]
	v_pk_add_f32 v[20:21], v[20:21], v[40:41]
	s_cbranch_vccnz .LBB0_1673
	global_store_dwordx4 v[36:37], v[22:25], off offset:512
	global_store_dwordx4 v[36:37], v[18:21], off offset:528

; __device__ __forceinline__ float blo(unsigned u) { return __uint_as_float(u << 16); }
; __device__ __forceinline__ float bhi(unsigned u) { return __uint_as_float(u & 0xffff0000u); }
; __device__ __forceinline__ unsigned pk2(float lo, float hi) { pk_f32x2_t v = {lo, hi}; pk_bf16x2_t b = __builtin_convertvector(v, pk_bf16x2_t); return __builtin_bit_cast(unsigned, b); }
;     __device__ __forceinline__ void operator()(const pg8::f32x4 (&acc)[2][2][4][2], const pg8::Unit& u, int wr, int wc, int fr, int fq) const {
;     ...
;                 for (int bj = 0; bj < 2; ++bj) { const size_t o = off + bj * 128; f32x4 xa, xc;
;                     if (xin) { xa = *(const f32x4*)(xin + o); xc = *(const f32x4*)(xin + o + 4); }
;                     else { const u32x4 r4 = *(const u32x4*)(xin_b + o); xa[0] = blo(r4.x); xa[1] = bhi(r4.x); xa[2] = blo(r4.y); xa[3] = bhi(r4.y); xc[0] = blo(r4.z); xc[1] = bhi(r4.z); xc[2] = blo(r4.w); xc[3] = bhi(r4.w); }
;                     f32x4 va, vc;
;                     va[0] = xa[0] + acc[ai][bj][m][0][0]; va[1] = xa[1] + acc[ai][bj][m][0][1]; va[2] = xa[2] + acc[ai][bj][m][0][2]; va[3] = xa[3] + acc[ai][bj][m][0][3];
;                     vc[0] = xc[0] + acc[ai][bj][m][1][0]; vc[1] = xc[1] + acc[ai][bj][m][1][1]; vc[2] = xc[2] + acc[ai][bj][m][1][2]; vc[3] = xc[3] + acc[ai][bj][m][1][3];
;                     if (xout) { *(f32x4*)(xout + o) = va; *(f32x4*)(xout + o + 4) = vc; }
;                     if (xb) { u32x4 w; w.x = pk2(va[0], va[1]); w.y = pk2(va[2], va[3]); w.z = pk2(vc[0], vc[1]); w.w = pk2(vc[2], vc[3]); *(u32x4*)(xb + o) = w; }
.LBB0_1677:
	v_add_u32_e32 v18, 0xb0, v154
	v_ashrrev_i32_e32 v19, 31, v18
	v_lshlrev_b64 v[20:21], 10, v[18:19]
	v_lshl_add_u64 v[22:23], v[20:21], 0, v[152:153]
	v_lshl_add_u64 v[24:25], v[22:23], 1, s[28:29]
	s_nop 1
	s_and_b64 vcc, exec, s[40:41]
	v_lshlrev_b32_e32 v20, 16, v178
	v_and_b32_e32 v21, 0xffff0000, v178
	v_pk_add_f32 v[14:15], v[14:15], v[20:21]
	v_lshlrev_b32_e32 v20, 16, v179
	v_and_b32_e32 v21, 0xffff0000, v179
	v_pk_add_f32 v[16:17], v[16:17], v[20:21]
	v_lshlrev_b32_e32 v20, 16, v180
	v_and_b32_e32 v21, 0xffff0000, v180
	v_pk_add_f32 v[10:11], v[10:11], v[20:21]
	v_lshlrev_b32_e32 v20, 16, v181
	v_and_b32_e32 v21, 0xffff0000, v181
	v_pk_add_f32 v[12:13], v[12:13], v[20:21]
	v_lshl_add_u64 v[20:21], v[22:23], 2, s[8:9]
	s_cbranch_vccnz .LBB0_1679
	global_store_dwordx4 v[20:21], v[14:17], off
	global_store_dwordx4 v[20:21], v[10:13], off offset:16

; __device__ __forceinline__ float blo(unsigned u) { return __uint_as_float(u << 16); }
; __device__ __forceinline__ float bhi(unsigned u) { return __uint_as_float(u & 0xffff0000u); }
; __device__ __forceinline__ unsigned pk2(float lo, float hi) { pk_f32x2_t v = {lo, hi}; pk_bf16x2_t b = __builtin_convertvector(v, pk_bf16x2_t); return __builtin_bit_cast(unsigned, b); }
;     __device__ __forceinline__ void operator()(const pg8::f32x4 (&acc)[2][2][4][2], const pg8::Unit& u, int wr, int wc, int fr, int fq) const {
;     ...
;                 for (int bj = 0; bj < 2; ++bj) { const size_t o = off + bj * 128; f32x4 xa, xc;
;                     if (xin) { xa = *(const f32x4*)(xin + o); xc = *(const f32x4*)(xin + o + 4); }
;                     else { const u32x4 r4 = *(const u32x4*)(xin_b + o); xa[0] = blo(r4.x); xa[1] = bhi(r4.x); xa[2] = blo(r4.y); xa[3] = bhi(r4.y); xc[0] = blo(r4.z); xc[1] = bhi(r4.z); xc[2] = blo(r4.w); xc[3] = bhi(r4.w); }
;                     f32x4 va, vc;
;                     va[0] = xa[0] + acc[ai][bj][m][0][0]; va[1] = xa[1] + acc[ai][bj][m][0][1]; va[2] = xa[2] + acc[ai][bj][m][0][2]; va[3] = xa[3] + acc[ai][bj][m][0][3];
;                     vc[0] = xc[0] + acc[ai][bj][m][1][0]; vc[1] = xc[1] + acc[ai][bj][m][1][1]; vc[2] = xc[2] + acc[ai][bj][m][1][2]; vc[3] = xc[3] + acc[ai][bj][m][1][3];
;                     if (xout) { *(f32x4*)(xout + o) = va; *(f32x4*)(xout + o + 4) = vc; }
;                     if (xb) { u32x4 w; w.x = pk2(va[0], va[1]); w.y = pk2(va[2], va[3]); w.z = pk2(vc[0], vc[1]); w.w = pk2(vc[2], vc[3]); *(u32x4*)(xb + o) = w; }
.LBB0_1681:
	v_lshlrev_b64 v[22:23], 1, v[22:23]
	v_or_b32_e32 v22, 0x100, v22
	v_lshl_add_u64 v[22:23], s[28:29], 0, v[22:23]
	s_nop 1
	s_and_b64 vcc, exec, s[40:41]
	v_lshlrev_b32_e32 v28, 16, v182
	v_and_b32_e32 v29, 0xffff0000, v182
	v_lshlrev_b32_e32 v24, 16, v183
	v_and_b32_e32 v25, 0xffff0000, v183
	v_pk_add_f32 v[8:9], v[8:9], v[24:25]
	v_lshlrev_b32_e32 v24, 16, v184
	v_and_b32_e32 v25, 0xffff0000, v184
	v_pk_add_f32 v[2:3], v[2:3], v[24:25]
	v_lshlrev_b32_e32 v24, 16, v185
	v_and_b32_e32 v25, 0xffff0000, v185
	v_pk_add_f32 v[6:7], v[6:7], v[28:29]
	v_pk_add_f32 v[4:5], v[4:5], v[24:25]
	s_cbranch_vccnz .LBB0_1683
	global_store_dwordx4 v[20:21], v[6:9], off offset:512
	global_store_dwordx4 v[20:21], v[2:5], off offset:528

; #define LAS __attribute__((address_space(3)))
; __global__ void __launch_bounds__(512, 2) fwd_kernel(Params p) {
;     extern __shared__ __attribute__((aligned(16))) unsigned char lds_raw[];
;     cg::grid_group grid = cg::this_grid();
;     LAS unsigned char* lds = (LAS unsigned char*)lds_raw;
	.amdhsa_kernel _Z10fwd_kernel6Params
		.amdhsa_group_segment_fixed_size 0
		.amdhsa_private_segment_fixed_size 0
		.amdhsa_kernarg_size 456
		.amdhsa_user_sgpr_count 2
		.amdhsa_user_sgpr_dispatch_ptr 0
		.amdhsa_user_sgpr_queue_ptr 0
		.amdhsa_user_sgpr_kernarg_segment_ptr 1
		.amdhsa_user_sgpr_dispatch_id 0
		.amdhsa_user_sgpr_kernarg_preload_length 0
		.amdhsa_user_sgpr_kernarg_preload_offset 0
		.amdhsa_user_sgpr_private_segment_size 0
		.amdhsa_uses_dynamic_stack 0
		.amdhsa_enable_private_segment 0
		.amdhsa_system_sgpr_workgroup_id_x 1
		.amdhsa_system_sgpr_workgroup_id_y 0
		.amdhsa_system_sgpr_workgroup_id_z 0
		.amdhsa_system_sgpr_workgroup_info 0
		.amdhsa_system_vgpr_workitem_id 2
		.amdhsa_next_free_vgpr 256
		.amdhsa_next_free_sgpr 100
		.amdhsa_accum_offset 256
		.amdhsa_reserve_vcc 1
		.amdhsa_float_round_mode_32 0
		.amdhsa_float_round_mode_16_64 0
		.amdhsa_float_denorm_mode_32 3
		.amdhsa_float_denorm_mode_16_64 3
		.amdhsa_dx10_clamp 1
		.amdhsa_ieee_mode 1
		.amdhsa_fp16_overflow 0
		.amdhsa_tg_split 0
		.amdhsa_exception_fp_ieee_invalid_op 0
		.amdhsa_exception_fp_denorm_src 0
		.amdhsa_exception_fp_ieee_div_zero 0
		.amdhsa_exception_fp_ieee_overflow 0
		.amdhsa_exception_fp_ieee_underflow 0
		.amdhsa_exception_fp_ieee_inexact 0
		.amdhsa_exception_int_div_zero 0
	.end_amdhsa_kernel

; #define LAS __attribute__((address_space(3)))
; __global__ void __launch_bounds__(512, 2) fwd_kernel(Params p) {
;     extern __shared__ __attribute__((aligned(16))) unsigned char lds_raw[];
;     cg::grid_group grid = cg::this_grid();
;     LAS unsigned char* lds = (LAS unsigned char*)lds_raw;
amdhsa.kernels:
  - .agpr_count:     0
    .args:
      - .offset:         0
        .size:           200
        .value_kind:     by_value
      - .offset:         200
        .size:           4
        .value_kind:     hidden_block_count_x
      - .offset:         204
        .size:           4
        .value_kind:     hidden_block_count_y
      - .offset:         208
        .size:           4
        .value_kind:     hidden_block_count_z
      - .offset:         212
        .size:           2
        .value_kind:     hidden_group_size_x
      - .offset:         214
        .size:           2
        .value_kind:     hidden_group_size_y
      - .offset:         216
        .size:           2
        .value_kind:     hidden_group_size_z
      - .offset:         218
        .size:           2
        .value_kind:     hidden_remainder_x
      - .offset:         220
        .size:           2
        .value_kind:     hidden_remainder_y
      - .offset:         222
        .size:           2
        .value_kind:     hidden_remainder_z
      - .offset:         240
        .size:           8
        .value_kind:     hidden_global_offset_x
      - .offset:         248
        .size:           8
        .value_kind:     hidden_global_offset_y
      - .offset:         256
        .size:           8
        .value_kind:     hidden_global_offset_z
      - .offset:         264
        .size:           2
        .value_kind:     hidden_grid_dims
      - .offset:         288
        .size:           8
        .value_kind:     hidden_multigrid_sync_arg
      - .offset:         320
        .size:           4
        .value_kind:     hidden_dynamic_lds_size
    .group_segment_fixed_size: 0
    .kernarg_segment_align: 8
    .kernarg_segment_size: 456
    .language:       OpenCL C
    .language_version:
      - 2
      - 0
    .max_flat_workgroup_size: 512
    .name:           _Z10fwd_kernel6Params
    .private_segment_fixed_size: 0
    .sgpr_count:     106
    .sgpr_spill_count: 216
    .symbol:         _Z10fwd_kernel6Params.kd
    .uniform_work_group_size: 1
    .uses_dynamic_stack: false
    .vgpr_count:     256
    .vgpr_spill_count: 0
    .wavefront_size: 64
